# lever 7: the 36 shfl_xor(1,2,4) steps of the SWA RMS-norm reductions use DPP (quad_perm / row_half_mirror) instead of ds_bpermute LDS round trips (bit-exact)
# speedup vs baseline: 1.0077x; 1.0077x over previous
; __device__ __forceinline__ unsigned cvt_pk_bf16(float lo, float hi) { unsigned r; asm volatile("v_cvt_pk_bf16_f32 %0, %1, %2" : "=v"(r) : "v"(lo), "v"(hi)); return r; }
; __device__ __forceinline__ float bflo(unsigned w) { return __uint_as_float(w << 16); }
; __device__ __forceinline__ float bfhi(unsigned w) { return __uint_as_float(w & 0xffff0000u); }
; #define LAS __attribute__((address_space(3)))
; __device__ __forceinline__ void swa_compute(SwaRaw& R, int b, int kvh, int nb, const bf16_t* P, const float* __restrict__ qg, const float* __restrict__ kg, const float* __restrict__ sinks, bf16_t* OB, LAS unsigned char* lds, int tid) {
;     ...
;         const f32x4 g0 = *(const f32x4*)(kg + ch * 8), g1 = *(const f32x4*)(kg + ch * 8 + 4);
; #pragma unroll
;         for (int p = 0; p < 4; ++p) { const int ki = (tid >> 3) + 64 * p; const u32x4 raw = R.k[p], rv = R.v[p];
;             float x[8] = {bflo(raw.x), bfhi(raw.x), bflo(raw.y), bfhi(raw.y), bflo(raw.z), bfhi(raw.z), bflo(raw.w), bfhi(raw.w)};
;             float ss = 0.f;
; #pragma unroll
;             for (int e = 0; e < 8; ++e) ss += x[e] * x[e];
;             ss += __shfl_xor(ss, 1); ss += __shfl_xor(ss, 2); ss += __shfl_xor(ss, 4);
;             const float rs = 1.0f / sqrtf(ss * (1.0f / 64.0f) + EPS);
;             u32x4 w; w.x = cvt_pk_bf16(x[0] * rs * g0.x, x[1] * rs * g0.y); w.y = cvt_pk_bf16(x[2] * rs * g0.z, x[3] * rs * g0.w); w.z = cvt_pk_bf16(x[4] * rs * g1.x, x[5] * rs * g1.y); w.w = cvt_pk_bf16(x[6] * rs * g1.z, x[7] * rs * g1.w);
;             *(LAS u32x4*)(Ks + ki * 72 + ch * 8) = w;
;             *(LAS u32x4*)(Vr + ki * 72 + ch * 8) = rv; }
.LBB0_404:
	global_load_dwordx4 v[40:43], v[112:113], off offset:16
	s_nop 0
	global_load_dwordx4 v[44:47], v[112:113], off
	v_and_b32_e32 v50, 64, v199
	v_xor_b32_e32 v51, 1, v199
	v_add_u32_e32 v50, 64, v50
	v_cmp_lt_i32_e32 vcc, v51, v50
	v_and_b32_e32 v54, 0xffff0000, v36
	v_mul_f32_e32 v58, v54, v54
	v_cndmask_b32_e32 v51, v199, v51, vcc
	v_lshlrev_b32_e32 v60, 2, v51
	v_xor_b32_e32 v51, 2, v199
	v_cmp_lt_i32_e32 vcc, v51, v50
	v_lshlrev_b32_e32 v55, 16, v37
	v_and_b32_e32 v56, 0xffff0000, v37
	v_cndmask_b32_e32 v51, v199, v51, vcc
	v_lshlrev_b32_e32 v61, 2, v51
	v_xor_b32_e32 v51, 4, v199
	v_cmp_lt_i32_e32 vcc, v51, v50
	v_lshlrev_b32_e32 v57, 16, v38
	v_and_b32_e32 v38, 0xffff0000, v38
	v_cndmask_b32_e32 v51, v199, v51, vcc
	v_lshlrev_b32_e32 v62, 2, v51
	v_lshlrev_b32_e32 v51, 16, v36
	v_fmac_f32_e32 v58, v51, v51
	v_fmac_f32_e32 v58, v55, v55
	v_fmac_f32_e32 v58, v56, v56
	v_fmac_f32_e32 v58, v57, v57
	v_and_b32_e32 v52, 0xffff0000, v39
	v_lshlrev_b32_e32 v53, 16, v39
	v_fmac_f32_e32 v58, v38, v38
	v_pk_mul_f32 v[36:37], v[52:53], v[52:53]
	s_and_b32 s0, s18, 3
	v_add_f32_e32 v37, v37, v58
	v_add_f32_e32 v36, v36, v37
	s_nop 1
	v_mov_b32_dpp v37, v36 quad_perm:[1,0,3,2] row_mask:0xf bank_mask:0xf
	v_readlane_b32 s4, v236, 23
	s_lshl_b32 s2, s0, 4
	v_readlane_b32 s8, v236, 27
	v_readlane_b32 s9, v236, 28
	s_waitcnt lgkmcnt(0)
	v_add_f32_e32 v36, v36, v37
	s_nop 1
	v_mov_b32_dpp v37, v36 quad_perm:[2,3,0,1] row_mask:0xf bank_mask:0xf
	s_add_u32 s2, s8, s2
	v_readlane_b32 s5, v236, 24
	s_addc_u32 s3, s9, 0
	s_and_b32 s4, s39, 31
	s_waitcnt lgkmcnt(0)
	v_add_f32_e32 v36, v36, v37
	s_nop 1
	v_mov_b32_dpp v37, v36 row_half_mirror row_mask:0xf bank_mask:0xf
	s_lshl_b32 s96, s4, 7
	v_readlane_b32 s6, v236, 25
	v_readfirstlane_b32 s6, v186
	s_lshr_b32 s8, s6, 6
	s_waitcnt lgkmcnt(0)
	v_add_f32_e32 v36, v36, v37
	v_fmamk_f32 v36, v36, 0x3c800000, v196
	v_cmp_gt_f32_e32 vcc, s90, v36
	v_mul_f32_e32 v37, 0x4f800000, v36
	s_lshl_b32 s0, s0, 9
	v_cndmask_b32_e32 v36, v36, v37, vcc
	v_sqrt_f32_e32 v37, v36
	v_readlane_b32 s16, v236, 35
	v_readlane_b32 s7, v236, 26
	v_readlane_b32 s14, v236, 33
	v_add_u32_e32 v39, -1, v37
	v_fma_f32 v58, -v39, v37, v36
	v_cmp_ge_f32_e64 s[4:5], 0, v58
	v_add_u32_e32 v58, 1, v37
	s_mul_i32 s7, s8, 0x1500
	v_cndmask_b32_e64 v39, v37, v39, s[4:5]
	v_fma_f32 v37, -v58, v37, v36
	v_cmp_lt_f32_e64 s[4:5], 0, v37
	s_movk_i32 s14, 0x7f
	s_movk_i32 s76, 0x7e
	v_cndmask_b32_e64 v37, v39, v58, s[4:5]
	v_mul_f32_e32 v39, 0x37800000, v37
	v_cndmask_b32_e32 v37, v37, v39, vcc
	v_cmp_class_f32_e32 vcc, v36, v197
	v_readlane_b32 s10, v236, 29
	v_readlane_b32 s11, v236, 30
	v_cndmask_b32_e32 v36, v37, v36, vcc
	v_div_scale_f32 v37, s[4:5], v36, v36, 1.0
	v_rcp_f32_e32 v39, v37
	v_readlane_b32 s12, v236, 31
	v_readlane_b32 s13, v236, 32
	v_readlane_b32 s15, v236, 34
	v_fma_f32 v58, -v37, v39, 1.0
	v_fmac_f32_e32 v39, v58, v39
	v_div_scale_f32 v58, vcc, 1.0, v36, 1.0
	v_mul_f32_e32 v59, v58, v39
	v_fma_f32 v63, -v37, v59, v58
	v_fmac_f32_e32 v59, v63, v39
	v_fma_f32 v37, -v37, v59, v58
	v_div_fmas_f32 v37, v37, v39, v59
	v_div_fixup_f32 v39, v37, v36, 1.0
	v_mul_f32_e32 v36, v39, v51
	v_mul_f32_e32 v37, v39, v54
	s_waitcnt vmcnt(0)
	v_mul_f32_e32 v36, v44, v36
	v_mul_f32_e32 v37, v45, v37
	v_cvt_pk_bf16_f32 v36, v36, v37
	v_mul_f32_e32 v37, v39, v55
	v_mul_f32_e32 v51, v39, v56
	v_mul_f32_e32 v37, v46, v37
	v_mul_f32_e32 v51, v47, v51
	v_cvt_pk_bf16_f32 v37, v37, v51
	v_mul_f32_e32 v51, v39, v57
	v_mul_f32_e32 v38, v39, v38
	v_mul_f32_e32 v51, v40, v51
	v_mul_f32_e32 v38, v41, v38
	v_cvt_pk_bf16_f32 v38, v51, v38
	v_mul_f32_e32 v51, v39, v53
	v_mul_f32_e32 v39, v39, v52
	v_mul_f32_e32 v39, v43, v39
	v_mul_f32_e32 v51, v42, v51
	v_cvt_pk_bf16_f32 v39, v51, v39
	ds_write_b128 v93, v[36:39] offset:18432
	ds_write_b128 v93, v[32:35] offset:55296
	v_and_b32_e32 v35, 0xffff0000, v28
	v_lshlrev_b32_e32 v34, 16, v28
	v_mul_f32_e32 v39, v35, v35
	v_lshlrev_b32_e32 v36, 16, v29
	v_fmac_f32_e32 v39, v34, v34
	v_and_b32_e32 v37, 0xffff0000, v29
	v_fmac_f32_e32 v39, v36, v36
	v_lshlrev_b32_e32 v38, 16, v30
	v_fmac_f32_e32 v39, v37, v37
	v_and_b32_e32 v30, 0xffff0000, v30
	v_fmac_f32_e32 v39, v38, v38
	v_and_b32_e32 v32, 0xffff0000, v31
	v_lshlrev_b32_e32 v33, 16, v31
	v_fmac_f32_e32 v39, v30, v30
	v_pk_mul_f32 v[28:29], v[32:33], v[32:33]
	v_add_u32_e32 v63, s7, v195
	v_add_f32_e32 v29, v29, v39
	v_add_f32_e32 v28, v28, v29
	s_nop 1
	v_mov_b32_dpp v29, v28 quad_perm:[1,0,3,2] row_mask:0xf bank_mask:0xf
	v_readlane_b32 s17, v236, 36
	v_readlane_b32 s18, v236, 37
	v_readlane_b32 s19, v236, 38
	v_writelane_b32 v235, s39, 9
	s_waitcnt lgkmcnt(0)
	v_add_f32_e32 v28, v28, v29
	s_nop 1
	v_mov_b32_dpp v29, v28 quad_perm:[2,3,0,1] row_mask:0xf bank_mask:0xf
	v_mov_b32_e32 v48, s0
	v_mov_b32_e32 v49, v99
	s_waitcnt lgkmcnt(0)
	v_add_f32_e32 v28, v28, v29
	s_nop 1
	v_mov_b32_dpp v29, v28 row_half_mirror row_mask:0xf bank_mask:0xf
	s_waitcnt lgkmcnt(0)
; __device__ __forceinline__ unsigned cvt_pk_bf16(float lo, float hi) { unsigned r; asm volatile("v_cvt_pk_bf16_f32 %0, %1, %2" : "=v"(r) : "v"(lo), "v"(hi)); return r; }
; __device__ __forceinline__ float bflo(unsigned w) { return __uint_as_float(w << 16); }
; __device__ __forceinline__ float bfhi(unsigned w) { return __uint_as_float(w & 0xffff0000u); }
; #define LAS __attribute__((address_space(3)))
; __device__ __forceinline__ void swa_compute(SwaRaw& R, int b, int kvh, int nb, const bf16_t* P, const float* __restrict__ qg, const float* __restrict__ kg, const float* __restrict__ sinks, bf16_t* OB, LAS unsigned char* lds, int tid) {
;     ...
;         for (int p = 0; p < 4; ++p) { const int ki = (tid >> 3) + 64 * p; const u32x4 raw = R.k[p], rv = R.v[p];
;             float x[8] = {bflo(raw.x), bfhi(raw.x), bflo(raw.y), bfhi(raw.y), bflo(raw.z), bfhi(raw.z), bflo(raw.w), bfhi(raw.w)};
;             float ss = 0.f;
; #pragma unroll
;             for (int e = 0; e < 8; ++e) ss += x[e] * x[e];
;             ss += __shfl_xor(ss, 1); ss += __shfl_xor(ss, 2); ss += __shfl_xor(ss, 4);
;             const float rs = 1.0f / sqrtf(ss * (1.0f / 64.0f) + EPS);
;             u32x4 w; w.x = cvt_pk_bf16(x[0] * rs * g0.x, x[1] * rs * g0.y); w.y = cvt_pk_bf16(x[2] * rs * g0.z, x[3] * rs * g0.w); w.z = cvt_pk_bf16(x[4] * rs * g1.x, x[5] * rs * g1.y); w.w = cvt_pk_bf16(x[6] * rs * g1.z, x[7] * rs * g1.w);
;             *(LAS u32x4*)(Ks + ki * 72 + ch * 8) = w;
;             *(LAS u32x4*)(Vr + ki * 72 + ch * 8) = rv; }
	v_add_f32_e32 v28, v28, v29
	v_fmamk_f32 v28, v28, 0x3c800000, v196
	v_cmp_gt_f32_e32 vcc, s90, v28
	v_mul_f32_e32 v29, 0x4f800000, v28
	s_nop 0
	v_cndmask_b32_e32 v28, v28, v29, vcc
	v_sqrt_f32_e32 v29, v28
	s_nop 0
	v_add_u32_e32 v31, -1, v29
	v_fma_f32 v39, -v31, v29, v28
	v_cmp_ge_f32_e64 s[4:5], 0, v39
	v_add_u32_e32 v39, 1, v29
	s_nop 0
	v_cndmask_b32_e64 v31, v29, v31, s[4:5]
	v_fma_f32 v29, -v39, v29, v28
	v_cmp_lt_f32_e64 s[4:5], 0, v29
	s_nop 1
	v_cndmask_b32_e64 v29, v31, v39, s[4:5]
	v_mul_f32_e32 v31, 0x37800000, v29
	v_cndmask_b32_e32 v29, v29, v31, vcc
	v_cmp_class_f32_e32 vcc, v28, v197
	s_nop 1
	v_cndmask_b32_e32 v28, v29, v28, vcc
	v_div_scale_f32 v29, s[4:5], v28, v28, 1.0
	v_rcp_f32_e32 v31, v29
	s_nop 0
	v_fma_f32 v39, -v29, v31, 1.0
	v_fmac_f32_e32 v31, v39, v31
	v_div_scale_f32 v39, vcc, 1.0, v28, 1.0
	v_mul_f32_e32 v51, v39, v31
	v_fma_f32 v52, -v29, v51, v39
	v_fmac_f32_e32 v51, v52, v31
	v_fma_f32 v29, -v29, v51, v39
	v_div_fmas_f32 v29, v29, v31, v51
	v_div_fixup_f32 v31, v29, v28, 1.0
	v_mul_f32_e32 v28, v31, v34
	v_mul_f32_e32 v29, v31, v35
	v_mul_f32_e32 v28, v44, v28
	v_mul_f32_e32 v29, v45, v29
	v_cvt_pk_bf16_f32 v28, v28, v29
	v_mul_f32_e32 v29, v31, v36
	v_mul_f32_e32 v34, v31, v37
	v_mul_f32_e32 v29, v46, v29
	v_mul_f32_e32 v34, v47, v34
	v_cvt_pk_bf16_f32 v29, v29, v34
	v_mul_f32_e32 v34, v31, v38
	v_mul_f32_e32 v30, v31, v30
	v_mul_f32_e32 v33, v31, v33
	v_mul_f32_e32 v31, v31, v32
	v_mul_f32_e32 v30, v41, v30
	v_mul_f32_e32 v31, v43, v31
	v_mul_f32_e32 v34, v40, v34
	v_cvt_pk_bf16_f32 v30, v34, v30
	v_mul_f32_e32 v33, v42, v33
	v_cvt_pk_bf16_f32 v31, v33, v31
	ds_write_b128 v93, v[28:31] offset:27648
	ds_write_b128 v93, v[24:27] offset:64512
	v_and_b32_e32 v27, 0xffff0000, v20
	v_lshlrev_b32_e32 v26, 16, v20
	v_mul_f32_e32 v31, v27, v27
	v_lshlrev_b32_e32 v28, 16, v21
	v_fmac_f32_e32 v31, v26, v26
	v_and_b32_e32 v29, 0xffff0000, v21
	v_fmac_f32_e32 v31, v28, v28
	v_lshlrev_b32_e32 v30, 16, v22
	v_fmac_f32_e32 v31, v29, v29
	v_and_b32_e32 v22, 0xffff0000, v22
	v_fmac_f32_e32 v31, v30, v30
	v_and_b32_e32 v24, 0xffff0000, v23
	v_lshlrev_b32_e32 v25, 16, v23
	v_fmac_f32_e32 v31, v22, v22
	v_pk_mul_f32 v[20:21], v[24:25], v[24:25]
	s_nop 0
	v_add_f32_e32 v21, v21, v31
	v_add_f32_e32 v20, v20, v21
	s_nop 1
	v_mov_b32_dpp v21, v20 quad_perm:[1,0,3,2] row_mask:0xf bank_mask:0xf
	s_waitcnt lgkmcnt(0)
	v_add_f32_e32 v20, v20, v21
	s_nop 1
	v_mov_b32_dpp v21, v20 quad_perm:[2,3,0,1] row_mask:0xf bank_mask:0xf
	s_waitcnt lgkmcnt(0)
	v_add_f32_e32 v20, v20, v21
	s_nop 1
	v_mov_b32_dpp v21, v20 row_half_mirror row_mask:0xf bank_mask:0xf
	s_waitcnt lgkmcnt(0)
	v_add_f32_e32 v20, v20, v21
	v_fmamk_f32 v20, v20, 0x3c800000, v196
	v_cmp_gt_f32_e32 vcc, s90, v20
	v_mul_f32_e32 v21, 0x4f800000, v20
	s_nop 0
	v_cndmask_b32_e32 v20, v20, v21, vcc
	v_sqrt_f32_e32 v21, v20
	s_nop 0
	v_add_u32_e32 v23, -1, v21
	v_fma_f32 v31, -v23, v21, v20
	v_cmp_ge_f32_e64 s[4:5], 0, v31
	v_add_u32_e32 v31, 1, v21
	s_nop 0
	v_cndmask_b32_e64 v23, v21, v23, s[4:5]
	v_fma_f32 v21, -v31, v21, v20
	v_cmp_lt_f32_e64 s[4:5], 0, v21
	s_nop 1
	v_cndmask_b32_e64 v21, v23, v31, s[4:5]
	v_mul_f32_e32 v23, 0x37800000, v21
	v_cndmask_b32_e32 v21, v21, v23, vcc
	v_cmp_class_f32_e32 vcc, v20, v197
	s_nop 1
	v_cndmask_b32_e32 v20, v21, v20, vcc
	v_div_scale_f32 v21, s[4:5], v20, v20, 1.0
	v_rcp_f32_e32 v23, v21
	s_nop 0
	v_fma_f32 v31, -v21, v23, 1.0
	v_fmac_f32_e32 v23, v31, v23
	v_div_scale_f32 v31, vcc, 1.0, v20, 1.0
	v_mul_f32_e32 v32, v31, v23
	v_fma_f32 v33, -v21, v32, v31
	v_fmac_f32_e32 v32, v33, v23
	v_fma_f32 v21, -v21, v32, v31
	v_div_fmas_f32 v21, v21, v23, v32
	v_div_fixup_f32 v23, v21, v20, 1.0
	v_mul_f32_e32 v20, v23, v26
	v_mul_f32_e32 v21, v23, v27
	v_mul_f32_e32 v20, v44, v20
	v_mul_f32_e32 v21, v45, v21
	v_cvt_pk_bf16_f32 v20, v20, v21
	v_mul_f32_e32 v21, v23, v28
	v_mul_f32_e32 v26, v23, v29
	v_mul_f32_e32 v21, v46, v21
	v_mul_f32_e32 v26, v47, v26
	v_cvt_pk_bf16_f32 v21, v21, v26
	v_mul_f32_e32 v26, v23, v30
	v_mul_f32_e32 v22, v23, v22
	v_mul_f32_e32 v25, v23, v25
	v_mul_f32_e32 v23, v23, v24
	v_mul_f32_e32 v22, v41, v22
	v_mul_f32_e32 v23, v43, v23
	v_mul_f32_e32 v26, v40, v26
	v_cvt_pk_bf16_f32 v22, v26, v22
	v_mul_f32_e32 v25, v42, v25
	v_cvt_pk_bf16_f32 v23, v25, v23
	ds_write_b128 v93, v[20:23] offset:36864
	ds_write_b128 v191, v[16:19] offset:18432
	v_and_b32_e32 v19, 0xffff0000, v12
	v_lshlrev_b32_e32 v18, 16, v12
	v_mul_f32_e32 v23, v19, v19
	v_lshlrev_b32_e32 v20, 16, v13
	v_fmac_f32_e32 v23, v18, v18
	v_and_b32_e32 v21, 0xffff0000, v13
	v_fmac_f32_e32 v23, v20, v20
	v_lshlrev_b32_e32 v22, 16, v14
	v_fmac_f32_e32 v23, v21, v21
	v_and_b32_e32 v14, 0xffff0000, v14
	v_fmac_f32_e32 v23, v22, v22
	v_and_b32_e32 v16, 0xffff0000, v15
	v_lshlrev_b32_e32 v17, 16, v15
	v_fmac_f32_e32 v23, v14, v14
	v_pk_mul_f32 v[12:13], v[16:17], v[16:17]
	s_nop 0
	v_add_f32_e32 v13, v13, v23
	v_add_f32_e32 v12, v12, v13
	s_nop 1
	v_mov_b32_dpp v13, v12 quad_perm:[1,0,3,2] row_mask:0xf bank_mask:0xf
	s_waitcnt lgkmcnt(0)
	v_add_f32_e32 v12, v12, v13
	s_nop 1
	v_mov_b32_dpp v13, v12 quad_perm:[2,3,0,1] row_mask:0xf bank_mask:0xf
	s_waitcnt lgkmcnt(0)
	v_add_f32_e32 v12, v12, v13
	s_nop 1
	v_mov_b32_dpp v13, v12 row_half_mirror row_mask:0xf bank_mask:0xf
	s_waitcnt lgkmcnt(0)
; __device__ __forceinline__ unsigned cvt_pk_bf16(float lo, float hi) { unsigned r; asm volatile("v_cvt_pk_bf16_f32 %0, %1, %2" : "=v"(r) : "v"(lo), "v"(hi)); return r; }
; __device__ __forceinline__ float bflo(unsigned w) { return __uint_as_float(w << 16); }
; __device__ __forceinline__ float bfhi(unsigned w) { return __uint_as_float(w & 0xffff0000u); }
; #define LAS __attribute__((address_space(3)))
; __device__ __forceinline__ void swa_compute(SwaRaw& R, int b, int kvh, int nb, const bf16_t* P, const float* __restrict__ qg, const float* __restrict__ kg, const float* __restrict__ sinks, bf16_t* OB, LAS unsigned char* lds, int tid) {
;     ...
;         for (int p = 0; p < 4; ++p) { const int ki = (tid >> 3) + 64 * p; const u32x4 raw = R.k[p], rv = R.v[p];
;             float x[8] = {bflo(raw.x), bfhi(raw.x), bflo(raw.y), bfhi(raw.y), bflo(raw.z), bfhi(raw.z), bflo(raw.w), bfhi(raw.w)};
;             float ss = 0.f;
; #pragma unroll
;             for (int e = 0; e < 8; ++e) ss += x[e] * x[e];
;             ss += __shfl_xor(ss, 1); ss += __shfl_xor(ss, 2); ss += __shfl_xor(ss, 4);
;             const float rs = 1.0f / sqrtf(ss * (1.0f / 64.0f) + EPS);
;             u32x4 w; w.x = cvt_pk_bf16(x[0] * rs * g0.x, x[1] * rs * g0.y); w.y = cvt_pk_bf16(x[2] * rs * g0.z, x[3] * rs * g0.w); w.z = cvt_pk_bf16(x[4] * rs * g1.x, x[5] * rs * g1.y); w.w = cvt_pk_bf16(x[6] * rs * g1.z, x[7] * rs * g1.w);
;             *(LAS u32x4*)(Ks + ki * 72 + ch * 8) = w;
;             *(LAS u32x4*)(Vr + ki * 72 + ch * 8) = rv; }
;     }
;     const f32x4 qg0 = *(const f32x4*)(qg + ch * 8), qg1 = *(const f32x4*)(qg + ch * 8 + 4);
;     ...
;         const int qi = wid * 16 + fr; const float sink = sinks[hq]; float m = sink;
; #pragma unroll
;         for (int j = 0; j < 10; ++j)
; #pragma unroll
;             for (int r = 0; r < 4; ++r) { const int ki = (kt0 + j) * 16 + 4 * fq + r; const bool valid = (ki > qi) && (ki <= qi + 128) && ((nb > 0) || (ki >= 128));
;                 s[j][r] = valid ? s[j][r] : -INFINITY; m = fmaxf(m, s[j][r]); }
	v_add_f32_e32 v12, v12, v13
	v_fmamk_f32 v12, v12, 0x3c800000, v196
	v_cmp_gt_f32_e32 vcc, s90, v12
	v_mul_f32_e32 v13, 0x4f800000, v12
	s_nop 0
	v_cndmask_b32_e32 v12, v12, v13, vcc
	v_sqrt_f32_e32 v13, v12
	s_nop 0
	v_add_u32_e32 v15, -1, v13
	v_fma_f32 v23, -v15, v13, v12
	v_cmp_ge_f32_e64 s[4:5], 0, v23
	v_add_u32_e32 v23, 1, v13
	s_nop 0
	v_cndmask_b32_e64 v15, v13, v15, s[4:5]
	v_fma_f32 v13, -v23, v13, v12
	v_cmp_lt_f32_e64 s[4:5], 0, v13
	s_nop 1
	v_cndmask_b32_e64 v13, v15, v23, s[4:5]
	v_mul_f32_e32 v15, 0x37800000, v13
	v_cndmask_b32_e32 v13, v13, v15, vcc
	v_cmp_class_f32_e32 vcc, v12, v197
	s_nop 1
	v_cndmask_b32_e32 v12, v13, v12, vcc
	v_div_scale_f32 v13, s[4:5], v12, v12, 1.0
	v_rcp_f32_e32 v15, v13
	s_lshl_b32 s4, s8, 4
	s_movk_i32 s5, 0x90
	v_fma_f32 v23, -v13, v15, 1.0
	v_fmac_f32_e32 v15, v23, v15
	v_div_scale_f32 v23, vcc, 1.0, v12, 1.0
	v_mul_f32_e32 v24, v23, v15
	v_fma_f32 v25, -v13, v24, v23
	v_fmac_f32_e32 v24, v25, v15
	v_fma_f32 v13, -v13, v24, v23
	v_div_fmas_f32 v13, v13, v15, v24
	v_div_fixup_f32 v15, v13, v12, 1.0
	v_mul_f32_e32 v12, v15, v18
	v_mul_f32_e32 v13, v15, v19
	v_mul_f32_e32 v12, v44, v12
	v_mul_f32_e32 v13, v45, v13
	v_cvt_pk_bf16_f32 v12, v12, v13
	v_mul_f32_e32 v13, v15, v20
	v_mul_f32_e32 v18, v15, v21
	v_mul_f32_e32 v13, v46, v13
	v_mul_f32_e32 v18, v47, v18
	v_cvt_pk_bf16_f32 v13, v13, v18
	v_mul_f32_e32 v18, v15, v22
	v_mul_f32_e32 v14, v15, v14
	v_mul_f32_e32 v17, v15, v17
	v_mul_f32_e32 v15, v15, v16
	v_or_b32_e32 v16, s4, v91
	s_add_i32 s4, s4, -16
	s_cmp_gt_u32 s6, 63
	s_cselect_b32 s4, s4, 0
	v_mul_f32_e32 v14, v41, v14
	v_mul_f32_e32 v17, v42, v17
	v_mul_f32_e32 v15, v43, v15
	v_add_u32_e32 v19, s4, v192
	s_add_i32 s16, s4, 16
	s_add_i32 s24, s4, 32
	s_add_i32 s34, s4, 48
	s_add_i32 s42, s4, 64
	s_add_i32 s50, s4, 0x50
	s_add_i32 s58, s4, 0x60
	s_add_i32 s66, s4, 0x70
	v_sub_co_u32_e32 v29, vcc, s4, v200
	s_add_i32 s78, s4, 0x90
	v_mul_f32_e32 v18, v40, v18
	v_cvt_pk_bf16_f32 v14, v18, v14
	v_cvt_pk_bf16_f32 v15, v17, v15
	v_add_u32_e32 v17, 0x80, v16
	v_mul_lo_u32 v64, v19, s5
	v_or_b32_e32 v19, s4, v91
	v_or_b32_e32 v20, s16, v91
	v_or_b32_e32 v21, s24, v91
	v_or_b32_e32 v22, s34, v91
	v_or_b32_e32 v23, s42, v91
	v_or_b32_e32 v24, s50, v91
	v_or_b32_e32 v25, s58, v91
	v_or_b32_e32 v26, s66, v91
	v_or_b32_e32 v27, v29, v91
	v_or_b32_e32 v28, s78, v91
	v_or_b32_e32 v30, s4, v161
	v_mul_lo_u32 v18, v16, s5
	v_mul_lo_u32 v19, v19, s5
	v_mul_lo_u32 v20, v20, s5
	v_mul_lo_u32 v21, v21, s5
	v_mul_lo_u32 v22, v22, s5
	v_mul_lo_u32 v23, v23, s5
	v_mul_lo_u32 v24, v24, s5
	v_mul_lo_u32 v25, v25, s5
	v_mul_lo_u32 v26, v26, s5
	v_mul_lo_u32 v27, v27, s5
	v_mul_lo_u32 v28, v28, s5
	v_cmp_gt_i32_e64 s[4:5], v30, v16
	v_cmp_le_i32_e64 s[6:7], v30, v17
	s_and_b64 s[6:7], s[4:5], s[6:7]
	v_cmp_lt_i32_e64 s[4:5], s14, v30
	s_or_b64 s[4:5], s[74:75], s[4:5]
	s_and_b64 s[4:5], s[6:7], s[4:5]
	v_cmp_ge_i32_e64 s[6:7], v30, v16
	v_cmp_lt_i32_e64 s[8:9], v30, v17
	s_and_b64 s[8:9], s[6:7], s[8:9]
	v_cmp_lt_i32_e64 s[6:7], s76, v30
	s_or_b64 s[6:7], s[74:75], s[6:7]
	v_or_b32_e32 v31, 2, v30
	s_and_b64 s[6:7], s[8:9], s[6:7]
	v_cmp_gt_i32_e64 s[8:9], v31, v16
	v_cmp_le_i32_e64 s[10:11], v31, v17
	s_and_b64 s[10:11], s[8:9], s[10:11]
	v_cmp_lt_i32_e64 s[8:9], s14, v31
	s_or_b64 s[8:9], s[74:75], s[8:9]
	v_or_b32_e32 v30, 3, v30
	s_and_b64 s[8:9], s[10:11], s[8:9]
	v_cmp_gt_i32_e64 s[10:11], v30, v16
	v_cmp_le_i32_e64 s[12:13], v30, v17
	s_and_b64 s[12:13], s[10:11], s[12:13]
	v_cmp_lt_i32_e64 s[10:11], s14, v30
	s_or_b64 s[10:11], s[74:75], s[10:11]
	v_or_b32_e32 v30, s16, v161
	s_and_b64 s[10:11], s[12:13], s[10:11]
	v_cmp_gt_i32_e64 s[12:13], v30, v16
	v_cmp_le_i32_e64 s[14:15], v30, v17
	s_and_b64 s[12:13], s[12:13], s[14:15]
	s_cmpk_gt_u32 s16, 0x7f
	s_cselect_b64 s[14:15], -1, 0
	s_or_b64 s[22:23], s[74:75], s[14:15]
	v_cmp_ge_i32_e64 s[14:15], v30, v16
	v_cmp_lt_i32_e64 s[16:17], v30, v17
	s_and_b64 s[16:17], s[14:15], s[16:17]
	v_cmp_lt_u32_e64 s[14:15], s76, v30
	s_or_b64 s[14:15], s[74:75], s[14:15]
	v_or_b32_e32 v31, 2, v30
	s_and_b64 s[14:15], s[16:17], s[14:15]
	v_cmp_gt_i32_e64 s[16:17], v31, v16
	v_cmp_le_i32_e64 s[18:19], v31, v17
	v_or_b32_e32 v30, 3, v30
	s_and_b64 s[16:17], s[16:17], s[18:19]
	v_cmp_gt_i32_e64 s[18:19], v30, v16
	v_cmp_le_i32_e64 s[20:21], v30, v17
	ds_write_b128 v93, v[12:15] offset:46080
	ds_write_b128 v191, v[8:11] offset:27648
	s_and_b64 s[18:19], s[18:19], s[20:21]
	v_or_b32_e32 v30, s24, v161
	global_load_dwordx4 v[8:11], v[114:115], off
	global_load_dwordx4 v[12:15], v[114:115], off offset:16
	s_and_b64 s[12:13], s[22:23], s[12:13]
	s_and_b64 s[16:17], s[22:23], s[16:17]
	s_and_b64 s[18:19], s[22:23], s[18:19]
	v_cmp_gt_i32_e64 s[20:21], v30, v16
	v_cmp_le_i32_e64 s[22:23], v30, v17
	s_and_b64 s[20:21], s[20:21], s[22:23]
	s_cmpk_gt_u32 s24, 0x7f
	s_cselect_b64 s[22:23], -1, 0
	s_or_b64 s[30:31], s[74:75], s[22:23]
	v_cmp_ge_i32_e64 s[22:23], v30, v16
	v_cmp_lt_i32_e64 s[24:25], v30, v17
	s_and_b64 s[24:25], s[22:23], s[24:25]
	v_cmp_lt_u32_e64 s[22:23], s76, v30
	s_or_b64 s[22:23], s[74:75], s[22:23]
	v_or_b32_e32 v31, 2, v30
	s_and_b64 s[22:23], s[24:25], s[22:23]
	v_cmp_gt_i32_e64 s[24:25], v31, v16
	v_cmp_le_i32_e64 s[26:27], v31, v17
	v_or_b32_e32 v30, 3, v30
	s_and_b64 s[24:25], s[24:25], s[26:27]
	v_cmp_gt_i32_e64 s[26:27], v30, v16
	v_cmp_le_i32_e64 s[28:29], v30, v17
	s_and_b64 s[26:27], s[26:27], s[28:29]
	v_or_b32_e32 v30, s34, v161
	s_and_b64 s[20:21], s[30:31], s[20:21]
	s_and_b64 s[24:25], s[30:31], s[24:25]
	s_and_b64 s[26:27], s[30:31], s[26:27]
	v_cmp_gt_i32_e64 s[28:29], v30, v16
	v_cmp_le_i32_e64 s[30:31], v30, v17
	s_and_b64 s[28:29], s[28:29], s[30:31]
; __device__ __forceinline__ void swa_compute(SwaRaw& R, int b, int kvh, int nb, const bf16_t* P, const float* __restrict__ qg, const float* __restrict__ kg, const float* __restrict__ sinks, bf16_t* OB, LAS unsigned char* lds, int tid) {
;     ...
;         const int qi = wid * 16 + fr; const float sink = sinks[hq]; float m = sink;
; #pragma unroll
;         for (int j = 0; j < 10; ++j)
; #pragma unroll
;             for (int r = 0; r < 4; ++r) { const int ki = (kt0 + j) * 16 + 4 * fq + r; const bool valid = (ki > qi) && (ki <= qi + 128) && ((nb > 0) || (ki >= 128));
;                 s[j][r] = valid ? s[j][r] : -INFINITY; m = fmaxf(m, s[j][r]); }
;         m = fmaxf(m, __shfl_xor(m, 16)); m = fmaxf(m, __shfl_xor(m, 32));
	s_cmpk_gt_u32 s34, 0x7f
	s_cselect_b64 s[30:31], -1, 0
	s_or_b64 s[40:41], s[74:75], s[30:31]
	v_cmp_ge_i32_e64 s[30:31], v30, v16
	v_cmp_lt_i32_e64 s[34:35], v30, v17
	s_and_b64 s[34:35], s[30:31], s[34:35]
	v_cmp_lt_u32_e64 s[30:31], s76, v30
	s_or_b64 s[30:31], s[74:75], s[30:31]
	v_or_b32_e32 v31, 2, v30
	s_and_b64 s[30:31], s[34:35], s[30:31]
	v_cmp_gt_i32_e64 s[34:35], v31, v16
	v_cmp_le_i32_e64 s[36:37], v31, v17
	v_or_b32_e32 v30, 3, v30
	s_and_b64 s[34:35], s[34:35], s[36:37]
	v_cmp_gt_i32_e64 s[36:37], v30, v16
	v_cmp_le_i32_e64 s[38:39], v30, v17
	s_and_b64 s[36:37], s[36:37], s[38:39]
	v_or_b32_e32 v30, s42, v161
	s_and_b64 s[28:29], s[40:41], s[28:29]
	s_and_b64 s[34:35], s[40:41], s[34:35]
	s_and_b64 s[36:37], s[40:41], s[36:37]
	v_cmp_gt_i32_e64 s[38:39], v30, v16
	v_cmp_le_i32_e64 s[40:41], v30, v17
	s_and_b64 s[38:39], s[38:39], s[40:41]
	s_cmpk_gt_u32 s42, 0x7f
	s_cselect_b64 s[40:41], -1, 0
	s_or_b64 s[48:49], s[74:75], s[40:41]
	v_cmp_ge_i32_e64 s[40:41], v30, v16
	v_cmp_lt_i32_e64 s[42:43], v30, v17
	s_and_b64 s[42:43], s[40:41], s[42:43]
	v_cmp_lt_u32_e64 s[40:41], s76, v30
	s_or_b64 s[40:41], s[74:75], s[40:41]
	v_or_b32_e32 v31, 2, v30
	s_and_b64 s[40:41], s[42:43], s[40:41]
	v_cmp_gt_i32_e64 s[42:43], v31, v16
	v_cmp_le_i32_e64 s[44:45], v31, v17
	v_or_b32_e32 v30, 3, v30
	s_and_b64 s[42:43], s[42:43], s[44:45]
	v_cmp_gt_i32_e64 s[44:45], v30, v16
	v_cmp_le_i32_e64 s[46:47], v30, v17
	s_and_b64 s[44:45], s[44:45], s[46:47]
	v_or_b32_e32 v30, s50, v161
	s_and_b64 s[38:39], s[48:49], s[38:39]
	s_and_b64 s[42:43], s[48:49], s[42:43]
	s_and_b64 s[44:45], s[48:49], s[44:45]
	v_cmp_gt_i32_e64 s[46:47], v30, v16
	v_cmp_le_i32_e64 s[48:49], v30, v17
	s_and_b64 s[46:47], s[46:47], s[48:49]
	s_cmpk_gt_u32 s50, 0x7f
	s_cselect_b64 s[48:49], -1, 0
	s_or_b64 s[56:57], s[74:75], s[48:49]
	v_cmp_ge_i32_e64 s[48:49], v30, v16
	v_cmp_lt_i32_e64 s[50:51], v30, v17
	s_and_b64 s[50:51], s[48:49], s[50:51]
	v_cmp_lt_u32_e64 s[48:49], s76, v30
	s_or_b64 s[48:49], s[74:75], s[48:49]
	v_or_b32_e32 v31, 2, v30
	s_and_b64 s[48:49], s[50:51], s[48:49]
	v_cmp_gt_i32_e64 s[50:51], v31, v16
	v_cmp_le_i32_e64 s[52:53], v31, v17
	v_or_b32_e32 v30, 3, v30
	s_and_b64 s[50:51], s[50:51], s[52:53]
	v_cmp_gt_i32_e64 s[52:53], v30, v16
	v_cmp_le_i32_e64 s[54:55], v30, v17
	s_and_b64 s[52:53], s[52:53], s[54:55]
	v_or_b32_e32 v30, s58, v161
	s_and_b64 s[46:47], s[56:57], s[46:47]
	s_and_b64 s[50:51], s[56:57], s[50:51]
	s_and_b64 s[52:53], s[56:57], s[52:53]
	v_cmp_gt_i32_e64 s[54:55], v30, v16
	v_cmp_le_i32_e64 s[56:57], v30, v17
	s_and_b64 s[54:55], s[54:55], s[56:57]
	s_cmpk_gt_u32 s58, 0x7f
	s_cselect_b64 s[56:57], -1, 0
	s_or_b64 s[64:65], s[74:75], s[56:57]
	v_cmp_ge_i32_e64 s[56:57], v30, v16
	v_cmp_lt_i32_e64 s[58:59], v30, v17
	s_and_b64 s[58:59], s[56:57], s[58:59]
	v_cmp_lt_u32_e64 s[56:57], s76, v30
	s_or_b64 s[56:57], s[74:75], s[56:57]
	v_or_b32_e32 v31, 2, v30
	s_and_b64 s[56:57], s[58:59], s[56:57]
	v_cmp_gt_i32_e64 s[58:59], v31, v16
	v_cmp_le_i32_e64 s[60:61], v31, v17
	v_or_b32_e32 v30, 3, v30
	s_and_b64 s[58:59], s[58:59], s[60:61]
	v_cmp_gt_i32_e64 s[60:61], v30, v16
	v_cmp_le_i32_e64 s[62:63], v30, v17
	s_and_b64 s[60:61], s[60:61], s[62:63]
	v_or_b32_e32 v30, s66, v161
	s_and_b64 s[54:55], s[64:65], s[54:55]
	s_and_b64 s[58:59], s[64:65], s[58:59]
	s_and_b64 s[60:61], s[64:65], s[60:61]
	v_cmp_gt_i32_e64 s[62:63], v30, v16
	v_cmp_le_i32_e64 s[64:65], v30, v17
	s_and_b64 s[62:63], s[62:63], s[64:65]
	s_cmpk_gt_u32 s66, 0x7f
	s_cselect_b64 s[64:65], -1, 0
	s_or_b64 s[72:73], s[74:75], s[64:65]
	v_cmp_ge_i32_e64 s[64:65], v30, v16
	v_cmp_lt_i32_e64 s[66:67], v30, v17
	s_and_b64 s[66:67], s[64:65], s[66:67]
	v_cmp_lt_u32_e64 s[64:65], s76, v30
	s_or_b64 s[64:65], s[74:75], s[64:65]
	v_or_b32_e32 v31, 2, v30
	s_and_b64 s[64:65], s[66:67], s[64:65]
	v_cmp_gt_i32_e64 s[66:67], v31, v16
	v_cmp_le_i32_e64 s[68:69], v31, v17
	v_or_b32_e32 v30, 3, v30
	s_and_b64 s[66:67], s[66:67], s[68:69]
	v_cmp_gt_i32_e64 s[68:69], v30, v16
	v_cmp_le_i32_e64 s[70:71], v30, v17
	s_and_b64 s[68:69], s[68:69], s[70:71]
	v_or_b32_e32 v29, v29, v161
	s_and_b64 s[62:63], s[72:73], s[62:63]
	s_and_b64 s[66:67], s[72:73], s[66:67]
	s_and_b64 s[68:69], s[72:73], s[68:69]
	v_cmp_gt_i32_e64 s[70:71], v29, v16
	v_cmp_le_i32_e64 s[72:73], v29, v17
	s_and_b64 s[70:71], s[70:71], s[72:73]
	s_or_b64 s[80:81], s[74:75], vcc
	v_cmp_ge_i32_e32 vcc, v29, v16
	v_cmp_lt_i32_e64 s[72:73], v29, v17
	s_and_b64 s[72:73], vcc, s[72:73]
	v_cmp_lt_u32_e32 vcc, s76, v29
	s_or_b64 s[74:75], s[74:75], vcc
	v_or_b32_e32 v30, 2, v29
	s_and_b64 s[72:73], s[72:73], s[74:75]
	v_cmp_gt_i32_e32 vcc, v30, v16
	v_cmp_le_i32_e64 s[74:75], v30, v17
	v_or_b32_e32 v29, 3, v29
	s_and_b64 s[74:75], vcc, s[74:75]
	v_cmp_gt_i32_e32 vcc, v29, v16
	v_cmp_le_i32_e64 s[76:77], v29, v17
	v_or_b32_e32 v29, s78, v161
	s_and_b64 s[76:77], vcc, s[76:77]
	v_cmp_gt_i32_e32 vcc, v29, v16
	v_cmp_le_i32_e64 s[78:79], v29, v17
	s_and_b64 s[70:71], s[80:81], s[70:71]
	s_and_b64 s[74:75], s[80:81], s[74:75]
	s_and_b64 s[76:77], s[80:81], s[76:77]
	s_and_b64 s[78:79], vcc, s[78:79]
	v_cmp_ge_i32_e32 vcc, v29, v16
	v_cmp_lt_i32_e64 s[80:81], v29, v17
	v_or_b32_e32 v30, 2, v29
	s_and_b64 s[80:81], vcc, s[80:81]
	v_cmp_gt_i32_e32 vcc, v30, v16
	v_cmp_le_i32_e64 s[82:83], v30, v17
	v_or_b32_e32 v29, 3, v29
	s_and_b64 s[82:83], vcc, s[82:83]
	v_cmp_gt_i32_e32 vcc, v29, v16
	v_cmp_le_i32_e64 s[84:85], v29, v17
	v_xor_b32_e32 v17, 16, v199
	s_and_b64 s[84:85], vcc, s[84:85]
	v_cmp_lt_i32_e32 vcc, v17, v50
	s_add_u32 s88, s88, s96
	s_addc_u32 s89, s89, 0
	v_cndmask_b32_e32 v17, v199, v17, vcc
	v_lshlrev_b32_e32 v65, 2, v17
	v_xor_b32_e32 v17, 32, v199
	v_cmp_lt_i32_e32 vcc, v17, v50
	v_lshl_add_u64 v[32:33], s[88:89], 0, v[88:89]
	v_add_u32_e32 v29, 0x3600, v64
	v_cndmask_b32_e32 v17, v199, v17, vcc
	v_lshlrev_b32_e32 v66, 2, v17
	v_mov_b32_e32 v17, v99
	s_movk_i32 vcc_lo, 0x4400
	v_lshl_add_u64 v[16:17], s[88:89], 0, v[16:17]
	v_mad_u64_u32 v[34:35], s[96:97], v32, vcc_lo, v[48:49]
	v_lshlrev_b64 v[16:17], 11, v[16:17]
	v_add_u32_e32 v30, 0x4800, v64
	v_mad_i32_i24 v35, v33, vcc_lo, v35
	v_or_b32_e32 v16, s0, v16
	v_lshl_add_u64 v[56:57], v[116:117], 0, v[34:35]
	v_lshl_add_u64 v[58:59], v[118:119], 0, v[16:17]
	s_mov_b64 s[96:97], 0
	v_add_u32_e32 v67, v184, v19
	v_add_u32_e32 v68, v184, v18
	v_add_u32_e32 v69, v184, v20
	v_add_u32_e32 v70, v184, v21
	v_add_u32_e32 v71, v184, v22
	v_add_u32_e32 v72, v184, v23
	v_add_u32_e32 v73, v184, v24
	v_add_u32_e32 v74, v184, v25
	v_add_u32_e32 v75, v184, v26
	v_add_u32_e32 v76, v184, v27
	v_add_u32_e32 v77, v184, v28
	v_add_u32_e32 v78, v193, v29
	v_add_u32_e32 v79, v193, v30
	s_waitcnt vmcnt(0)
	s_branch .LBB0_406

; __device__ __forceinline__ unsigned cvt_pk_bf16(float lo, float hi) { unsigned r; asm volatile("v_cvt_pk_bf16_f32 %0, %1, %2" : "=v"(r) : "v"(lo), "v"(hi)); return r; }
; __device__ __forceinline__ float bflo(unsigned w) { return __uint_as_float(w << 16); }
; __device__ __forceinline__ float bfhi(unsigned w) { return __uint_as_float(w & 0xffff0000u); }
; #define LAS __attribute__((address_space(3)))
; __device__ __forceinline__ void swa_compute(SwaRaw& R, int b, int kvh, int nb, const bf16_t* P, const float* __restrict__ qg, const float* __restrict__ kg, const float* __restrict__ sinks, bf16_t* OB, LAS unsigned char* lds, int tid) {
;     ...
;         for (int p = 0; p < 2; ++p) { const int row = (tid >> 3) + 64 * p; const u32x4 raw = R.q[p];
;             float x[8] = {bflo(raw.x), bfhi(raw.x), bflo(raw.y), bfhi(raw.y), bflo(raw.z), bfhi(raw.z), bflo(raw.w), bfhi(raw.w)};
;             float ss = 0.f;
; #pragma unroll
;             for (int e = 0; e < 8; ++e) ss += x[e] * x[e];
;             ss += __shfl_xor(ss, 1); ss += __shfl_xor(ss, 2); ss += __shfl_xor(ss, 4);
;             const float rs = 0.125f / sqrtf(ss * (1.0f / 64.0f) + EPS);
;             u32x4 w; w.x = cvt_pk_bf16(x[0] * rs * qg0.x, x[1] * rs * qg0.y); w.y = cvt_pk_bf16(x[2] * rs * qg0.z, x[3] * rs * qg0.w); w.z = cvt_pk_bf16(x[4] * rs * qg1.x, x[5] * rs * qg1.y); w.w = cvt_pk_bf16(x[6] * rs * qg1.z, x[7] * rs * qg1.w);
;             *(LAS u32x4*)(Qs + row * 72 + ch * 8) = w; }
;         if (g < 3) {
; #pragma unroll
;             for (int p = 0; p < 2; ++p) R.q[p] = *(const u32x4*)(P + (rq0 + (tid >> 3) + 64 * p) * PLD + 3072 + (hq + 1) * 64 + ch * 8);
;         }
.LBB0_406:
	s_waitcnt vmcnt(4)
	v_and_b32_e32 v19, 0xffff0000, v0
	v_lshlrev_b32_e32 v18, 16, v0
	v_mul_f32_e32 v26, v19, v19
	v_lshlrev_b32_e32 v22, 16, v1
	v_fmac_f32_e32 v26, v18, v18
	v_and_b32_e32 v23, 0xffff0000, v1
	v_fmac_f32_e32 v26, v22, v22
	v_lshlrev_b32_e32 v24, 16, v2
	v_fmac_f32_e32 v26, v23, v23
	v_and_b32_e32 v25, 0xffff0000, v2
	v_fmac_f32_e32 v26, v24, v24
	v_and_b32_e32 v20, 0xffff0000, v3
	v_lshlrev_b32_e32 v21, 16, v3
	v_fmac_f32_e32 v26, v25, v25
	v_pk_mul_f32 v[16:17], v[20:21], v[20:21]
	s_cmpk_eq_i32 s96, 0x180
	v_add_f32_e32 v17, v17, v26
	v_add_f32_e32 v16, v16, v17
	s_nop 1
	v_mov_b32_dpp v17, v16 quad_perm:[1,0,3,2] row_mask:0xf bank_mask:0xf
	s_waitcnt lgkmcnt(0)
	v_add_f32_e32 v16, v16, v17
	s_nop 1
	v_mov_b32_dpp v17, v16 quad_perm:[2,3,0,1] row_mask:0xf bank_mask:0xf
	s_waitcnt lgkmcnt(0)
	v_add_f32_e32 v16, v16, v17
	s_nop 1
	v_mov_b32_dpp v17, v16 row_half_mirror row_mask:0xf bank_mask:0xf
	s_waitcnt lgkmcnt(0)
	v_add_f32_e32 v16, v16, v17
	v_fmamk_f32 v16, v16, 0x3c800000, v196
	v_cmp_gt_f32_e32 vcc, s90, v16
	v_mul_f32_e32 v17, 0x4f800000, v16
	s_nop 0
	v_cndmask_b32_e32 v16, v16, v17, vcc
	v_sqrt_f32_e32 v17, v16
	s_nop 0
	v_add_u32_e32 v26, -1, v17
	v_fma_f32 v27, -v26, v17, v16
	v_cmp_ge_f32_e64 s[88:89], 0, v27
	v_add_u32_e32 v27, 1, v17
	s_nop 0
	v_cndmask_b32_e64 v26, v17, v26, s[88:89]
	v_fma_f32 v17, -v27, v17, v16
	v_cmp_lt_f32_e64 s[88:89], 0, v17
	s_nop 1
	v_cndmask_b32_e64 v17, v26, v27, s[88:89]
	v_mul_f32_e32 v26, 0x37800000, v17
	v_cndmask_b32_e32 v17, v17, v26, vcc
	v_cmp_class_f32_e32 vcc, v16, v197
	s_nop 1
	v_cndmask_b32_e32 v16, v17, v16, vcc
	v_div_scale_f32 v17, s[88:89], v16, v16, s87
	v_rcp_f32_e32 v26, v17
	s_nop 0
	v_fma_f32 v27, -v17, v26, 1.0
	v_fmac_f32_e32 v26, v27, v26
	v_div_scale_f32 v27, vcc, s87, v16, s87
	v_mul_f32_e32 v28, v27, v26
	v_fma_f32 v29, -v17, v28, v27
	v_fmac_f32_e32 v28, v29, v26
	v_fma_f32 v17, -v17, v28, v27
	v_div_fmas_f32 v17, v17, v26, v28
	v_div_fixup_f32 v26, v17, v16, s87
	v_mul_f32_e32 v16, v26, v18
	v_mul_f32_e32 v17, v26, v19
	v_mul_f32_e32 v16, v8, v16
	v_mul_f32_e32 v17, v9, v17
	v_cvt_pk_bf16_f32 v16, v16, v17
	v_mul_f32_e32 v17, v26, v22
	v_mul_f32_e32 v18, v26, v23
	v_mul_f32_e32 v17, v10, v17
	v_mul_f32_e32 v18, v11, v18
	v_cvt_pk_bf16_f32 v17, v17, v18
	v_mul_f32_e32 v18, v26, v24
	v_mul_f32_e32 v19, v26, v25
	v_mul_f32_e32 v18, v12, v18
	v_mul_f32_e32 v19, v13, v19
	v_cvt_pk_bf16_f32 v18, v18, v19
	v_mul_f32_e32 v19, v26, v21
	v_mul_f32_e32 v19, v14, v19
	v_mul_f32_e32 v20, v26, v20
	v_mul_f32_e32 v20, v15, v20
	v_cvt_pk_bf16_f32 v19, v19, v20
	ds_write_b128 v198, v[16:19]
	v_and_b32_e32 v19, 0xffff0000, v4
	v_lshlrev_b32_e32 v18, 16, v4
	v_mul_f32_e32 v26, v19, v19
	v_lshlrev_b32_e32 v22, 16, v5
	v_fmac_f32_e32 v26, v18, v18
	v_and_b32_e32 v23, 0xffff0000, v5
	v_fmac_f32_e32 v26, v22, v22
	v_lshlrev_b32_e32 v24, 16, v6
	v_fmac_f32_e32 v26, v23, v23
	v_and_b32_e32 v25, 0xffff0000, v6
	v_fmac_f32_e32 v26, v24, v24
	v_and_b32_e32 v20, 0xffff0000, v7
	v_lshlrev_b32_e32 v21, 16, v7
	v_fmac_f32_e32 v26, v25, v25
	v_pk_mul_f32 v[16:17], v[20:21], v[20:21]
	s_nop 0
	v_add_f32_e32 v17, v17, v26
	v_add_f32_e32 v16, v16, v17
	s_nop 1
	v_mov_b32_dpp v17, v16 quad_perm:[1,0,3,2] row_mask:0xf bank_mask:0xf
	s_waitcnt lgkmcnt(0)
	v_add_f32_e32 v16, v16, v17
	s_nop 1
	v_mov_b32_dpp v17, v16 quad_perm:[2,3,0,1] row_mask:0xf bank_mask:0xf
	s_waitcnt lgkmcnt(0)
	v_add_f32_e32 v16, v16, v17
	s_nop 1
	v_mov_b32_dpp v17, v16 row_half_mirror row_mask:0xf bank_mask:0xf
	s_waitcnt lgkmcnt(0)
	v_add_f32_e32 v16, v16, v17
	v_fmamk_f32 v16, v16, 0x3c800000, v196
	v_cmp_gt_f32_e32 vcc, s90, v16
	v_mul_f32_e32 v17, 0x4f800000, v16
	s_nop 0
	v_cndmask_b32_e32 v16, v16, v17, vcc
	v_sqrt_f32_e32 v17, v16
	s_nop 0
	v_add_u32_e32 v26, -1, v17
	v_fma_f32 v27, -v26, v17, v16
	v_cmp_ge_f32_e64 s[88:89], 0, v27
	v_add_u32_e32 v27, 1, v17
	s_nop 0
	v_cndmask_b32_e64 v26, v17, v26, s[88:89]
	v_fma_f32 v17, -v27, v17, v16
	v_cmp_lt_f32_e64 s[88:89], 0, v17
	s_nop 1
	v_cndmask_b32_e64 v17, v26, v27, s[88:89]
	v_mul_f32_e32 v26, 0x37800000, v17
	v_cndmask_b32_e32 v17, v17, v26, vcc
	v_cmp_class_f32_e32 vcc, v16, v197
	s_nop 1
	v_cndmask_b32_e32 v16, v17, v16, vcc
	v_div_scale_f32 v17, s[88:89], v16, v16, s87
	v_rcp_f32_e32 v26, v17
	s_nop 0
	v_fma_f32 v27, -v17, v26, 1.0
	v_fmac_f32_e32 v26, v27, v26
	v_div_scale_f32 v27, vcc, s87, v16, s87
	v_mul_f32_e32 v28, v27, v26
	v_fma_f32 v29, -v17, v28, v27
	v_fmac_f32_e32 v28, v29, v26
	v_fma_f32 v17, -v17, v28, v27
	v_div_fmas_f32 v17, v17, v26, v28
	v_div_fixup_f32 v26, v17, v16, s87
	v_mul_f32_e32 v16, v26, v18
	v_mul_f32_e32 v17, v26, v19
	v_mul_f32_e32 v16, v8, v16
	v_mul_f32_e32 v17, v9, v17
	v_cvt_pk_bf16_f32 v16, v16, v17
	v_mul_f32_e32 v17, v26, v22
	v_mul_f32_e32 v18, v26, v23
	v_mul_f32_e32 v17, v10, v17
	v_mul_f32_e32 v18, v11, v18
	v_cvt_pk_bf16_f32 v17, v17, v18
	v_mul_f32_e32 v18, v26, v24
	v_mul_f32_e32 v19, v26, v25
	v_mul_f32_e32 v18, v12, v18
	v_mul_f32_e32 v19, v13, v19
	v_cvt_pk_bf16_f32 v18, v18, v19
	v_mul_f32_e32 v19, v26, v21
	v_mul_f32_e32 v19, v14, v19
	v_mul_f32_e32 v20, v26, v20
	v_mul_f32_e32 v20, v15, v20
	v_cvt_pk_bf16_f32 v19, v19, v20
	ds_write_b128 v198, v[16:19] offset:9216
	s_cbranch_scc1 .LBB0_405
	v_lshl_add_u64 v[0:1], v[56:57], 0, s[96:97]
	v_add_co_u32_e32 v2, vcc, 0xb801000, v0
	s_nop 1
	v_addc_co_u32_e32 v3, vcc, 0, v1, vcc
	v_add_co_u32_e32 v4, vcc, 0xb911000, v0
	s_nop 1
	v_addc_co_u32_e32 v5, vcc, 0, v1, vcc
	global_load_dwordx4 v[0:3], v[2:3], off offset:2176
	s_nop 0
	global_load_dwordx4 v[4:7], v[4:5], off offset:2176
	s_branch .LBB0_405

; __device__ __forceinline__ void swa_load(SwaRaw& R, int b, int kvh, int nb, const bf16_t* P, int tid) {
;     const size_t rq0 = (size_t)b * SEQ + (size_t)nb * 128; const int ch = tid & 7;
; #pragma unroll
;     for (int p = 0; p < 4; ++p) { const int ki = (tid >> 3) + 64 * p; const bool valid = (nb > 0) || (ki >= 128);
;         R.k[p] = (u32x4){0u, 0u, 0u, 0u}; R.v[p] = (u32x4){0u, 0u, 0u, 0u};
;         if (valid) { const size_t row = rq0 - 128 + ki; R.k[p] = *(const u32x4*)(P + row * PLD + 4096 + kvh * 64 + ch * 8); R.v[p] = *(const u32x4*)(P + row * PLD + 4352 + kvh * 64 + ch * 8); } }
; #pragma unroll
;     for (int p = 0; p < 2; ++p) R.q[p] = *(const u32x4*)(P + (rq0 + (tid >> 3) + 64 * p) * PLD + 3072 + (kvh * 4) * 64 + ch * 8);
; }
; __device__ __forceinline__ void swa_compute(SwaRaw& R, int b, int kvh, int nb, const bf16_t* P, const float* __restrict__ qg, const float* __restrict__ kg, const float* __restrict__ sinks, bf16_t* OB, LAS unsigned char* lds, int tid) {
;     const int lane = tid & 63, wid = __builtin_amdgcn_readfirstlane(tid >> 6), fr = lane & 15, fq = lane >> 4;
;     LAS bf16_t* Qs = (LAS bf16_t*)lds;
;     LAS bf16_t* Ks = Qs + 128 * 72;
;     LAS bf16_t* Vr = Ks + 256 * 72;
;     LAS bf16_t* Pw = Vr + 256 * 72 + wid * (16 * 168);
;     const size_t rq0 = (size_t)b * SEQ + (size_t)nb * 128;
;     const int ch = tid & 7;
;     {
;         const f32x4 g0 = *(const f32x4*)(kg + ch * 8), g1 = *(const f32x4*)(kg + ch * 8 + 4);
; #pragma unroll
;         for (int p = 0; p < 4; ++p) { const int ki = (tid >> 3) + 64 * p; const u32x4 raw = R.k[p], rv = R.v[p];
;             float x[8] = {bflo(raw.x), bfhi(raw.x), bflo(raw.y), bfhi(raw.y), bflo(raw.z), bfhi(raw.z), bflo(raw.w), bfhi(raw.w)};
;             float ss = 0.f;
; #pragma unroll
;             for (int e = 0; e < 8; ++e) ss += x[e] * x[e];
;             ss += __shfl_xor(ss, 1); ss += __shfl_xor(ss, 2); ss += __shfl_xor(ss, 4);
;             const float rs = 1.0f / sqrtf(ss * (1.0f / 64.0f) + EPS);
;             u32x4 w; w.x = cvt_pk_bf16(x[0] * rs * g0.x, x[1] * rs * g0.y); w.y = cvt_pk_bf16(x[2] * rs * g0.z, x[3] * rs * g0.w); w.z = cvt_pk_bf16(x[4] * rs * g1.x, x[5] * rs * g1.y); w.w = cvt_pk_bf16(x[6] * rs * g1.z, x[7] * rs * g1.w);
;             *(LAS u32x4*)(Ks + ki * 72 + ch * 8) = w;
;             *(LAS u32x4*)(Vr + ki * 72 + ch * 8) = rv; }
.LBB0_497:
	s_or_b64 exec, exec, s[2:3]
	v_readlane_b32 s12, v236, 23
	s_lshr_b32 s2, s92, 1
	v_readlane_b32 s13, v236, 24
	v_readlane_b32 s16, v236, 27
	v_readlane_b32 s17, v236, 28
	s_and_b32 s2, s2, 48
	s_mov_b64 s[12:13], s[16:17]
	s_add_u32 s2, s12, s2
	s_addc_u32 s3, s13, 0
	s_and_b32 s6, s94, 31
	s_lshl_b32 s89, s6, 7
	s_lshl_b32 s6, s92, 4
	v_lshl_add_u64 v[2:3], s[4:5], 0, v[104:105]
	v_mov_b64_e32 v[4:5], s[72:73]
	s_and_b32 s88, s6, 0x600
	v_mad_u64_u32 v[6:7], s[6:7], v2, s58, v[4:5]
	v_mov_b32_e32 v2, v7
	v_mad_u64_u32 v[2:3], s[6:7], v3, s58, v[2:3]
	v_mov_b32_e32 v7, v2
	s_lshl_b32 s96, s11, 1
	v_mov_b32_e32 v121, v1
	v_lshl_add_u64 v[2:3], v[6:7], 0, s[96:97]
	v_lshl_add_u64 v[2:3], v[2:3], 0, v[120:121]
	s_movk_i32 s6, 0x2000
	v_add_co_u32_e32 v2, vcc, s6, v2
	v_xor_b32_e32 v50, 1, v175
	s_nop 0
	v_addc_co_u32_e32 v3, vcc, 0, v3, vcc
	global_load_dwordx4 v[30:33], v[2:3], off
	global_load_dwordx4 v[26:29], v[2:3], off offset:512
	v_lshl_add_u64 v[2:3], s[4:5], 0, v[106:107]
	v_mad_u64_u32 v[6:7], s[4:5], v2, s58, v[4:5]
	v_mov_b32_e32 v2, v7
	v_mad_u64_u32 v[2:3], s[4:5], v3, s58, v[2:3]
	v_mov_b32_e32 v7, v2
	v_lshl_add_u64 v[2:3], v[6:7], 0, s[96:97]
	v_lshl_add_u64 v[2:3], v[2:3], 0, v[120:121]
	v_add_co_u32_e32 v2, vcc, s6, v2
	s_mul_i32 s6, s10, 0x4400
	s_nop 0
	v_addc_co_u32_e32 v3, vcc, 0, v3, vcc
	global_load_dwordx4 v[22:25], v[2:3], off
	global_load_dwordx4 v[10:13], v[2:3], off offset:512
	v_or_b32_e32 v2, s9, v88
	v_mad_u64_u32 v[2:3], s[4:5], v2, s58, v[4:5]
	v_add_u32_e32 v3, s6, v3
	s_lshl_b32 s96, s8, 9
	v_lshl_add_u64 v[2:3], v[2:3], 0, s[96:97]
	v_lshl_add_u64 v[6:7], v[2:3], 0, v[120:121]
	s_movk_i32 s4, 0x1000
	v_add_co_u32_e32 v2, vcc, s4, v6
	s_mov_b32 s4, 0x111000
	s_nop 0
	v_addc_co_u32_e32 v3, vcc, 0, v7, vcc
	v_add_co_u32_e32 v6, vcc, s4, v6
	global_load_dwordx4 v[2:5], v[2:3], off offset:2048
	s_nop 0
	v_addc_co_u32_e32 v7, vcc, 0, v7, vcc
	global_load_dwordx4 v[6:9], v[6:7], off offset:2048
	s_nop 0
	global_load_dwordx4 v[14:17], v[108:109], off offset:16
	global_load_dwordx4 v[18:21], v[108:109], off
	v_cmp_lt_i32_e32 vcc, v50, v76
	s_waitcnt vmcnt(9)
	v_and_b32_e32 v53, 0xffff0000, v46
	v_lshlrev_b32_e32 v52, 16, v46
	v_cndmask_b32_e32 v50, v175, v50, vcc
	v_lshlrev_b32_e32 v62, 2, v50
	v_xor_b32_e32 v50, 2, v175
	v_cmp_lt_i32_e32 vcc, v50, v76
	v_mul_f32_e32 v57, v53, v53
	v_lshlrev_b32_e32 v54, 16, v47
	v_cndmask_b32_e32 v50, v175, v50, vcc
	v_lshlrev_b32_e32 v63, 2, v50
	v_xor_b32_e32 v50, 4, v175
	v_fmac_f32_e32 v57, v52, v52
	v_cmp_lt_i32_e32 vcc, v50, v76
	v_and_b32_e32 v55, 0xffff0000, v47
	v_fmac_f32_e32 v57, v54, v54
	v_cndmask_b32_e32 v50, v175, v50, vcc
	v_lshlrev_b32_e32 v56, 16, v48
	v_fmac_f32_e32 v57, v55, v55
	v_lshlrev_b32_e32 v64, 2, v50
	v_and_b32_e32 v48, 0xffff0000, v48
	v_fmac_f32_e32 v57, v56, v56
	v_and_b32_e32 v50, 0xffff0000, v49
	v_lshlrev_b32_e32 v51, 16, v49
	v_fmac_f32_e32 v57, v48, v48
	v_pk_mul_f32 v[46:47], v[50:51], v[50:51]
	v_readfirstlane_b32 s6, v186
	v_add_f32_e32 v47, v47, v57
	v_add_f32_e32 v46, v46, v47
	s_nop 1
	v_mov_b32_dpp v47, v46 quad_perm:[1,0,3,2] row_mask:0xf bank_mask:0xf
	s_lshr_b32 s8, s6, 6
	v_readlane_b32 s14, v236, 25
	v_readlane_b32 s24, v236, 35
	s_mul_i32 s7, s8, 0x1500
	s_waitcnt lgkmcnt(0)
	v_add_f32_e32 v46, v46, v47
	s_nop 1
	v_mov_b32_dpp v47, v46 quad_perm:[2,3,0,1] row_mask:0xf bank_mask:0xf
	v_add_u32_e32 v65, s7, v171
	s_movk_i32 s14, 0x7f
	s_movk_i32 s76, 0x7e
	v_readlane_b32 s15, v236, 26
	s_waitcnt lgkmcnt(0)
	v_add_f32_e32 v46, v46, v47
	s_nop 1
	v_mov_b32_dpp v47, v46 row_half_mirror row_mask:0xf bank_mask:0xf
	v_readlane_b32 s22, v236, 33
	v_readlane_b32 s23, v236, 34
	v_readlane_b32 s18, v236, 29
	v_readlane_b32 s19, v236, 30
	s_waitcnt lgkmcnt(0)
	v_add_f32_e32 v46, v46, v47
	v_fmamk_f32 v46, v46, 0x3c800000, v95
	v_cmp_gt_f32_e32 vcc, s91, v46
	v_mul_f32_e32 v47, 0x4f800000, v46
	v_readlane_b32 s20, v236, 31
	v_cndmask_b32_e32 v46, v46, v47, vcc
	v_sqrt_f32_e32 v47, v46
	v_readlane_b32 s21, v236, 32
	v_readlane_b32 s25, v236, 36
	v_readlane_b32 s26, v236, 37
	v_add_u32_e32 v49, -1, v47
	v_fma_f32 v57, -v49, v47, v46
	v_cmp_ge_f32_e64 s[4:5], 0, v57
	v_add_u32_e32 v57, 1, v47
	v_readlane_b32 s27, v236, 38
	v_cndmask_b32_e64 v49, v47, v49, s[4:5]
	v_fma_f32 v47, -v57, v47, v46
	v_cmp_lt_f32_e64 s[4:5], 0, v47
	v_mov_b32_e32 v0, s88
	s_movk_i32 s96, 0x4400
	v_cndmask_b32_e64 v47, v49, v57, s[4:5]
	v_mul_f32_e32 v49, 0x37800000, v47
	v_cndmask_b32_e32 v47, v47, v49, vcc
	v_cmp_class_f32_e32 vcc, v46, v172
	s_nop 1
	v_cndmask_b32_e32 v46, v47, v46, vcc
	v_div_scale_f32 v47, s[4:5], v46, v46, 1.0
	v_rcp_f32_e32 v49, v47
	s_nop 0
	v_fma_f32 v57, -v47, v49, 1.0
	v_fmac_f32_e32 v49, v57, v49
	v_div_scale_f32 v57, vcc, 1.0, v46, 1.0
	v_mul_f32_e32 v58, v57, v49
	v_fma_f32 v59, -v47, v58, v57
	v_fmac_f32_e32 v58, v59, v49
	v_fma_f32 v47, -v47, v58, v57
	v_div_fmas_f32 v47, v47, v49, v58
	v_div_fixup_f32 v49, v47, v46, 1.0
	v_mul_f32_e32 v46, v49, v52
	v_mul_f32_e32 v47, v49, v53
	s_waitcnt vmcnt(0)
; __device__ __forceinline__ unsigned cvt_pk_bf16(float lo, float hi) { unsigned r; asm volatile("v_cvt_pk_bf16_f32 %0, %1, %2" : "=v"(r) : "v"(lo), "v"(hi)); return r; }
; __device__ __forceinline__ float bflo(unsigned w) { return __uint_as_float(w << 16); }
; __device__ __forceinline__ float bfhi(unsigned w) { return __uint_as_float(w & 0xffff0000u); }
; #define LAS __attribute__((address_space(3)))
; __device__ __forceinline__ void swa_compute(SwaRaw& R, int b, int kvh, int nb, const bf16_t* P, const float* __restrict__ qg, const float* __restrict__ kg, const float* __restrict__ sinks, bf16_t* OB, LAS unsigned char* lds, int tid) {
;     ...
;         for (int p = 0; p < 4; ++p) { const int ki = (tid >> 3) + 64 * p; const u32x4 raw = R.k[p], rv = R.v[p];
;             float x[8] = {bflo(raw.x), bfhi(raw.x), bflo(raw.y), bfhi(raw.y), bflo(raw.z), bfhi(raw.z), bflo(raw.w), bfhi(raw.w)};
;             float ss = 0.f;
; #pragma unroll
;             for (int e = 0; e < 8; ++e) ss += x[e] * x[e];
;             ss += __shfl_xor(ss, 1); ss += __shfl_xor(ss, 2); ss += __shfl_xor(ss, 4);
;             const float rs = 1.0f / sqrtf(ss * (1.0f / 64.0f) + EPS);
;             u32x4 w; w.x = cvt_pk_bf16(x[0] * rs * g0.x, x[1] * rs * g0.y); w.y = cvt_pk_bf16(x[2] * rs * g0.z, x[3] * rs * g0.w); w.z = cvt_pk_bf16(x[4] * rs * g1.x, x[5] * rs * g1.y); w.w = cvt_pk_bf16(x[6] * rs * g1.z, x[7] * rs * g1.w);
;             *(LAS u32x4*)(Ks + ki * 72 + ch * 8) = w;
;             *(LAS u32x4*)(Vr + ki * 72 + ch * 8) = rv; }
	v_mul_f32_e32 v46, v18, v46
	v_mul_f32_e32 v47, v19, v47
	v_cvt_pk_bf16_f32 v46, v46, v47
	v_mul_f32_e32 v47, v49, v54
	v_mul_f32_e32 v52, v49, v55
	v_mul_f32_e32 v47, v20, v47
	v_mul_f32_e32 v52, v21, v52
	v_cvt_pk_bf16_f32 v47, v47, v52
	v_mul_f32_e32 v52, v49, v56
	v_mul_f32_e32 v48, v49, v48
	v_mul_f32_e32 v51, v49, v51
	v_mul_f32_e32 v49, v49, v50
	v_mul_f32_e32 v48, v15, v48
	v_mul_f32_e32 v49, v17, v49
	v_mul_f32_e32 v52, v14, v52
	v_cvt_pk_bf16_f32 v48, v52, v48
	v_mul_f32_e32 v51, v16, v51
	v_cvt_pk_bf16_f32 v49, v51, v49
	ds_write_b128 v162, v[46:49] offset:18432
	ds_write_b128 v162, v[42:45] offset:55296
	v_and_b32_e32 v45, 0xffff0000, v38
	v_lshlrev_b32_e32 v44, 16, v38
	v_mul_f32_e32 v49, v45, v45
	v_lshlrev_b32_e32 v46, 16, v39
	v_fmac_f32_e32 v49, v44, v44
	v_and_b32_e32 v47, 0xffff0000, v39
	v_fmac_f32_e32 v49, v46, v46
	v_lshlrev_b32_e32 v48, 16, v40
	v_fmac_f32_e32 v49, v47, v47
	v_and_b32_e32 v40, 0xffff0000, v40
	v_fmac_f32_e32 v49, v48, v48
	v_and_b32_e32 v42, 0xffff0000, v41
	v_lshlrev_b32_e32 v43, 16, v41
	v_fmac_f32_e32 v49, v40, v40
	v_pk_mul_f32 v[38:39], v[42:43], v[42:43]
	s_nop 0
	v_add_f32_e32 v39, v39, v49
	v_add_f32_e32 v38, v38, v39
	s_nop 1
	v_mov_b32_dpp v39, v38 quad_perm:[1,0,3,2] row_mask:0xf bank_mask:0xf
	s_waitcnt lgkmcnt(0)
	v_add_f32_e32 v38, v38, v39
	s_nop 1
	v_mov_b32_dpp v39, v38 quad_perm:[2,3,0,1] row_mask:0xf bank_mask:0xf
	s_waitcnt lgkmcnt(0)
	v_add_f32_e32 v38, v38, v39
	s_nop 1
	v_mov_b32_dpp v39, v38 row_half_mirror row_mask:0xf bank_mask:0xf
	s_waitcnt lgkmcnt(0)
	v_add_f32_e32 v38, v38, v39
	v_fmamk_f32 v38, v38, 0x3c800000, v95
	v_cmp_gt_f32_e32 vcc, s91, v38
	v_mul_f32_e32 v39, 0x4f800000, v38
	s_nop 0
	v_cndmask_b32_e32 v38, v38, v39, vcc
	v_sqrt_f32_e32 v39, v38
	s_nop 0
	v_add_u32_e32 v41, -1, v39
	v_fma_f32 v49, -v41, v39, v38
	v_cmp_ge_f32_e64 s[4:5], 0, v49
	v_add_u32_e32 v49, 1, v39
	s_nop 0
	v_cndmask_b32_e64 v41, v39, v41, s[4:5]
	v_fma_f32 v39, -v49, v39, v38
	v_cmp_lt_f32_e64 s[4:5], 0, v39
	s_nop 1
	v_cndmask_b32_e64 v39, v41, v49, s[4:5]
	v_mul_f32_e32 v41, 0x37800000, v39
	v_cndmask_b32_e32 v39, v39, v41, vcc
	v_cmp_class_f32_e32 vcc, v38, v172
	s_nop 1
	v_cndmask_b32_e32 v38, v39, v38, vcc
	v_div_scale_f32 v39, s[4:5], v38, v38, 1.0
	v_rcp_f32_e32 v41, v39
	s_nop 0
	v_fma_f32 v49, -v39, v41, 1.0
	v_fmac_f32_e32 v41, v49, v41
	v_div_scale_f32 v49, vcc, 1.0, v38, 1.0
	v_mul_f32_e32 v50, v49, v41
	v_fma_f32 v51, -v39, v50, v49
	v_fmac_f32_e32 v50, v51, v41
	v_fma_f32 v39, -v39, v50, v49
	v_div_fmas_f32 v39, v39, v41, v50
	v_div_fixup_f32 v41, v39, v38, 1.0
	v_mul_f32_e32 v38, v41, v44
	v_mul_f32_e32 v39, v41, v45
	v_mul_f32_e32 v38, v18, v38
	v_mul_f32_e32 v39, v19, v39
	v_cvt_pk_bf16_f32 v38, v38, v39
	v_mul_f32_e32 v39, v41, v46
	v_mul_f32_e32 v44, v41, v47
	v_mul_f32_e32 v39, v20, v39
	v_mul_f32_e32 v44, v21, v44
	v_cvt_pk_bf16_f32 v39, v39, v44
	v_mul_f32_e32 v44, v41, v48
	v_mul_f32_e32 v40, v41, v40
	v_mul_f32_e32 v43, v41, v43
	v_mul_f32_e32 v41, v41, v42
	v_mul_f32_e32 v40, v15, v40
	v_mul_f32_e32 v41, v17, v41
	v_mul_f32_e32 v44, v14, v44
	v_cvt_pk_bf16_f32 v40, v44, v40
	v_mul_f32_e32 v43, v16, v43
	v_cvt_pk_bf16_f32 v41, v43, v41
	ds_write_b128 v162, v[38:41] offset:27648
	ds_write_b128 v162, v[34:37] offset:64512
	v_and_b32_e32 v37, 0xffff0000, v30
	v_lshlrev_b32_e32 v36, 16, v30
	v_mul_f32_e32 v41, v37, v37
	v_lshlrev_b32_e32 v38, 16, v31
	v_fmac_f32_e32 v41, v36, v36
	v_and_b32_e32 v39, 0xffff0000, v31
	v_fmac_f32_e32 v41, v38, v38
	v_lshlrev_b32_e32 v40, 16, v32
	v_fmac_f32_e32 v41, v39, v39
	v_and_b32_e32 v32, 0xffff0000, v32
	v_fmac_f32_e32 v41, v40, v40
	v_and_b32_e32 v34, 0xffff0000, v33
	v_lshlrev_b32_e32 v35, 16, v33
	v_fmac_f32_e32 v41, v32, v32
	v_pk_mul_f32 v[30:31], v[34:35], v[34:35]
	s_nop 0
	v_add_f32_e32 v31, v31, v41
	v_add_f32_e32 v30, v30, v31
	s_nop 1
	v_mov_b32_dpp v31, v30 quad_perm:[1,0,3,2] row_mask:0xf bank_mask:0xf
	s_waitcnt lgkmcnt(0)
	v_add_f32_e32 v30, v30, v31
	s_nop 1
	v_mov_b32_dpp v31, v30 quad_perm:[2,3,0,1] row_mask:0xf bank_mask:0xf
	s_waitcnt lgkmcnt(0)
	v_add_f32_e32 v30, v30, v31
	s_nop 1
	v_mov_b32_dpp v31, v30 row_half_mirror row_mask:0xf bank_mask:0xf
	s_waitcnt lgkmcnt(0)
	v_add_f32_e32 v30, v30, v31
	v_fmamk_f32 v30, v30, 0x3c800000, v95
	v_cmp_gt_f32_e32 vcc, s91, v30
	v_mul_f32_e32 v31, 0x4f800000, v30
	s_nop 0
	v_cndmask_b32_e32 v30, v30, v31, vcc
	v_sqrt_f32_e32 v31, v30
	s_nop 0
	v_add_u32_e32 v33, -1, v31
	v_fma_f32 v41, -v33, v31, v30
	v_cmp_ge_f32_e64 s[4:5], 0, v41
	v_add_u32_e32 v41, 1, v31
	s_nop 0
	v_cndmask_b32_e64 v33, v31, v33, s[4:5]
	v_fma_f32 v31, -v41, v31, v30
	v_cmp_lt_f32_e64 s[4:5], 0, v31
	s_nop 1
	v_cndmask_b32_e64 v31, v33, v41, s[4:5]
	v_mul_f32_e32 v33, 0x37800000, v31
	v_cndmask_b32_e32 v31, v31, v33, vcc
	v_cmp_class_f32_e32 vcc, v30, v172
	s_nop 1
	v_cndmask_b32_e32 v30, v31, v30, vcc
	v_div_scale_f32 v31, s[4:5], v30, v30, 1.0
	v_rcp_f32_e32 v33, v31
	s_nop 0
	v_fma_f32 v41, -v31, v33, 1.0
	v_fmac_f32_e32 v33, v41, v33
	v_div_scale_f32 v41, vcc, 1.0, v30, 1.0
	v_mul_f32_e32 v42, v41, v33
	v_fma_f32 v43, -v31, v42, v41
	v_fmac_f32_e32 v42, v43, v33
	v_fma_f32 v31, -v31, v42, v41
	v_div_fmas_f32 v31, v31, v33, v42
	v_div_fixup_f32 v33, v31, v30, 1.0
	v_mul_f32_e32 v30, v33, v36
	v_mul_f32_e32 v31, v33, v37
	v_mul_f32_e32 v30, v18, v30
	v_mul_f32_e32 v31, v19, v31
	v_cvt_pk_bf16_f32 v30, v30, v31
	v_mul_f32_e32 v31, v33, v38
	v_mul_f32_e32 v36, v33, v39
	v_mul_f32_e32 v31, v20, v31
	v_mul_f32_e32 v36, v21, v36
	v_cvt_pk_bf16_f32 v31, v31, v36
	v_mul_f32_e32 v36, v33, v40
	v_mul_f32_e32 v32, v33, v32
	v_mul_f32_e32 v35, v33, v35
	v_mul_f32_e32 v33, v33, v34
	v_mul_f32_e32 v32, v15, v32
	v_mul_f32_e32 v33, v17, v33
	v_mul_f32_e32 v36, v14, v36
	v_cvt_pk_bf16_f32 v32, v36, v32
	v_mul_f32_e32 v35, v16, v35
	v_cvt_pk_bf16_f32 v33, v35, v33
	ds_write_b128 v162, v[30:33] offset:36864
	ds_write_b128 v163, v[26:29] offset:18432
	v_and_b32_e32 v27, 0xffff0000, v22
	v_lshlrev_b32_e32 v26, 16, v22
	v_mul_f32_e32 v32, v27, v27
	v_lshlrev_b32_e32 v28, 16, v23
	v_fmac_f32_e32 v32, v26, v26
	v_and_b32_e32 v29, 0xffff0000, v23
	v_fmac_f32_e32 v32, v28, v28
	v_lshlrev_b32_e32 v30, 16, v24
	v_fmac_f32_e32 v32, v29, v29
	v_and_b32_e32 v31, 0xffff0000, v24
	v_fmac_f32_e32 v32, v30, v30
	v_and_b32_e32 v22, 0xffff0000, v25
	v_lshlrev_b32_e32 v23, 16, v25
	v_fmac_f32_e32 v32, v31, v31
	v_pk_mul_f32 v[24:25], v[22:23], v[22:23]
	s_nop 0
	v_add_f32_e32 v25, v25, v32
	v_add_f32_e32 v24, v24, v25
	s_nop 1
	v_mov_b32_dpp v25, v24 quad_perm:[1,0,3,2] row_mask:0xf bank_mask:0xf
	s_waitcnt lgkmcnt(0)
; __device__ __forceinline__ unsigned cvt_pk_bf16(float lo, float hi) { unsigned r; asm volatile("v_cvt_pk_bf16_f32 %0, %1, %2" : "=v"(r) : "v"(lo), "v"(hi)); return r; }
; __device__ __forceinline__ float bflo(unsigned w) { return __uint_as_float(w << 16); }
; __device__ __forceinline__ float bfhi(unsigned w) { return __uint_as_float(w & 0xffff0000u); }
; #define LAS __attribute__((address_space(3)))
; __device__ __forceinline__ void swa_compute(SwaRaw& R, int b, int kvh, int nb, const bf16_t* P, const float* __restrict__ qg, const float* __restrict__ kg, const float* __restrict__ sinks, bf16_t* OB, LAS unsigned char* lds, int tid) {
;     ...
;         for (int p = 0; p < 4; ++p) { const int ki = (tid >> 3) + 64 * p; const u32x4 raw = R.k[p], rv = R.v[p];
;             float x[8] = {bflo(raw.x), bfhi(raw.x), bflo(raw.y), bfhi(raw.y), bflo(raw.z), bfhi(raw.z), bflo(raw.w), bfhi(raw.w)};
;             float ss = 0.f;
; #pragma unroll
;             for (int e = 0; e < 8; ++e) ss += x[e] * x[e];
;             ss += __shfl_xor(ss, 1); ss += __shfl_xor(ss, 2); ss += __shfl_xor(ss, 4);
;             const float rs = 1.0f / sqrtf(ss * (1.0f / 64.0f) + EPS);
;             u32x4 w; w.x = cvt_pk_bf16(x[0] * rs * g0.x, x[1] * rs * g0.y); w.y = cvt_pk_bf16(x[2] * rs * g0.z, x[3] * rs * g0.w); w.z = cvt_pk_bf16(x[4] * rs * g1.x, x[5] * rs * g1.y); w.w = cvt_pk_bf16(x[6] * rs * g1.z, x[7] * rs * g1.w);
;             *(LAS u32x4*)(Ks + ki * 72 + ch * 8) = w;
;             *(LAS u32x4*)(Vr + ki * 72 + ch * 8) = rv; }
;     }
;     const f32x4 qg0 = *(const f32x4*)(qg + ch * 8), qg1 = *(const f32x4*)(qg + ch * 8 + 4);
;     const int kt0 = wid > 0 ? wid - 1 : 0;
;     ...
;         const int qi = wid * 16 + fr; const float sink = sinks[hq]; float m = sink;
; #pragma unroll
;         for (int j = 0; j < 10; ++j)
; #pragma unroll
;             for (int r = 0; r < 4; ++r) { const int ki = (kt0 + j) * 16 + 4 * fq + r; const bool valid = (ki > qi) && (ki <= qi + 128) && ((nb > 0) || (ki >= 128));
;                 s[j][r] = valid ? s[j][r] : -INFINITY; m = fmaxf(m, s[j][r]); }
	v_add_f32_e32 v24, v24, v25
	s_nop 1
	v_mov_b32_dpp v25, v24 quad_perm:[2,3,0,1] row_mask:0xf bank_mask:0xf
	s_waitcnt lgkmcnt(0)
	v_add_f32_e32 v24, v24, v25
	s_nop 1
	v_mov_b32_dpp v25, v24 row_half_mirror row_mask:0xf bank_mask:0xf
	s_waitcnt lgkmcnt(0)
	v_add_f32_e32 v24, v24, v25
	v_fmamk_f32 v24, v24, 0x3c800000, v95
	v_cmp_gt_f32_e32 vcc, s91, v24
	v_mul_f32_e32 v25, 0x4f800000, v24
	s_nop 0
	v_cndmask_b32_e32 v24, v24, v25, vcc
	v_sqrt_f32_e32 v25, v24
	s_nop 0
	v_add_u32_e32 v32, -1, v25
	v_fma_f32 v33, -v32, v25, v24
	v_cmp_ge_f32_e64 s[4:5], 0, v33
	v_add_u32_e32 v33, 1, v25
	s_nop 0
	v_cndmask_b32_e64 v32, v25, v32, s[4:5]
	v_fma_f32 v25, -v33, v25, v24
	v_cmp_lt_f32_e64 s[4:5], 0, v25
	s_nop 1
	v_cndmask_b32_e64 v25, v32, v33, s[4:5]
	v_mul_f32_e32 v32, 0x37800000, v25
	v_cndmask_b32_e32 v25, v25, v32, vcc
	v_cmp_class_f32_e32 vcc, v24, v172
	s_nop 1
	v_cndmask_b32_e32 v24, v25, v24, vcc
	v_div_scale_f32 v25, s[4:5], v24, v24, 1.0
	v_rcp_f32_e32 v32, v25
	s_lshl_b32 s4, s8, 4
	v_fma_f32 v33, -v25, v32, 1.0
	v_fmac_f32_e32 v32, v33, v32
	v_div_scale_f32 v33, vcc, 1.0, v24, 1.0
	v_mul_f32_e32 v34, v33, v32
	v_fma_f32 v35, -v25, v34, v33
	v_fmac_f32_e32 v34, v35, v32
	v_fma_f32 v25, -v25, v34, v33
	v_div_fmas_f32 v25, v25, v32, v34
	v_div_fixup_f32 v24, v25, v24, 1.0
	v_mul_f32_e32 v25, v24, v26
	v_mul_f32_e32 v18, v18, v25
	v_mul_f32_e32 v25, v24, v27
	v_mul_f32_e32 v19, v19, v25
	v_cvt_pk_bf16_f32 v18, v18, v19
	v_mul_f32_e32 v19, v24, v28
	v_mul_f32_e32 v19, v20, v19
	v_mul_f32_e32 v20, v24, v29
	v_mul_f32_e32 v20, v21, v20
	v_cvt_pk_bf16_f32 v19, v19, v20
	v_mul_f32_e32 v20, v24, v30
	v_mul_f32_e32 v14, v14, v20
	v_mul_f32_e32 v20, v24, v31
	v_mul_f32_e32 v15, v15, v20
	v_cvt_pk_bf16_f32 v20, v14, v15
	v_mul_f32_e32 v14, v24, v23
	v_mul_f32_e32 v15, v24, v22
	v_mul_f32_e32 v14, v16, v14
	v_mul_f32_e32 v15, v17, v15
	v_cvt_pk_bf16_f32 v21, v14, v15
	ds_write_b128 v162, v[18:21] offset:46080
	ds_write_b128 v163, v[10:13] offset:27648
	v_or_b32_e32 v18, s4, v91
	s_add_i32 s4, s4, -16
	s_cmp_gt_u32 s6, 63
	s_cselect_b32 s4, s4, 0
	v_add_u32_e32 v19, 0x80, v18
	v_add_u32_e32 v21, s4, v164
	v_or_b32_e32 v32, s4, v161
	v_mul_lo_u32 v66, v21, s59
	v_or_b32_e32 v21, s4, v91
	s_add_i32 s16, s4, 16
	s_add_i32 s24, s4, 32
	s_add_i32 s34, s4, 48
	s_add_i32 s42, s4, 64
	s_add_i32 s50, s4, 0x50
	s_add_i32 s58, s4, 0x60
	s_add_i32 s66, s4, 0x70
	v_sub_co_u32_e32 v31, vcc, s4, v176
	s_add_i32 s78, s4, 0x90
	v_cmp_gt_i32_e64 s[4:5], v32, v18
	v_cmp_le_i32_e64 s[6:7], v32, v19
	s_and_b64 s[6:7], s[4:5], s[6:7]
	v_cmp_lt_i32_e64 s[4:5], s14, v32
	s_or_b64 s[4:5], s[74:75], s[4:5]
	s_and_b64 s[4:5], s[6:7], s[4:5]
	v_cmp_ge_i32_e64 s[6:7], v32, v18
	v_cmp_lt_i32_e64 s[8:9], v32, v19
	s_and_b64 s[8:9], s[6:7], s[8:9]
	v_cmp_lt_i32_e64 s[6:7], s76, v32
	s_or_b64 s[6:7], s[74:75], s[6:7]
	v_or_b32_e32 v33, 2, v32
	s_and_b64 s[6:7], s[8:9], s[6:7]
	v_cmp_gt_i32_e64 s[8:9], v33, v18
	v_cmp_le_i32_e64 s[10:11], v33, v19
	s_and_b64 s[10:11], s[8:9], s[10:11]
	v_cmp_lt_i32_e64 s[8:9], s14, v33
	s_or_b64 s[8:9], s[74:75], s[8:9]
	v_or_b32_e32 v32, 3, v32
	s_and_b64 s[8:9], s[10:11], s[8:9]
	v_cmp_gt_i32_e64 s[10:11], v32, v18
	v_cmp_le_i32_e64 s[12:13], v32, v19
	s_and_b64 s[12:13], s[10:11], s[12:13]
	v_cmp_lt_i32_e64 s[10:11], s14, v32
	s_or_b64 s[10:11], s[74:75], s[10:11]
	v_or_b32_e32 v32, s16, v161
	s_and_b64 s[10:11], s[12:13], s[10:11]
	v_cmp_gt_i32_e64 s[12:13], v32, v18
	v_cmp_le_i32_e64 s[14:15], v32, v19
	s_and_b64 s[12:13], s[12:13], s[14:15]
	s_cmpk_gt_u32 s16, 0x7f
	s_cselect_b64 s[14:15], -1, 0
	v_or_b32_e32 v22, s16, v91
	s_or_b64 s[22:23], s[74:75], s[14:15]
	v_cmp_ge_i32_e64 s[14:15], v32, v18
	v_cmp_lt_i32_e64 s[16:17], v32, v19
	s_and_b64 s[16:17], s[14:15], s[16:17]
	v_cmp_lt_u32_e64 s[14:15], s76, v32
	s_or_b64 s[14:15], s[74:75], s[14:15]
	v_or_b32_e32 v33, 2, v32
	global_load_dwordx4 v[10:13], v[110:111], off
	global_load_dwordx4 v[14:17], v[110:111], off offset:16
	s_and_b64 s[14:15], s[16:17], s[14:15]
	v_cmp_gt_i32_e64 s[16:17], v33, v18
	v_cmp_le_i32_e64 s[18:19], v33, v19
	v_or_b32_e32 v32, 3, v32
	s_and_b64 s[16:17], s[16:17], s[18:19]
	v_cmp_gt_i32_e64 s[18:19], v32, v18
	v_cmp_le_i32_e64 s[20:21], v32, v19
	s_and_b64 s[18:19], s[18:19], s[20:21]
	v_or_b32_e32 v32, s24, v161
	s_and_b64 s[12:13], s[22:23], s[12:13]
	s_and_b64 s[16:17], s[22:23], s[16:17]
	s_and_b64 s[18:19], s[22:23], s[18:19]
	v_cmp_gt_i32_e64 s[20:21], v32, v18
	v_cmp_le_i32_e64 s[22:23], v32, v19
	s_and_b64 s[20:21], s[20:21], s[22:23]
	s_cmpk_gt_u32 s24, 0x7f
	s_cselect_b64 s[22:23], -1, 0
	v_or_b32_e32 v23, s24, v91
	s_or_b64 s[30:31], s[74:75], s[22:23]
	v_cmp_ge_i32_e64 s[22:23], v32, v18
	v_cmp_lt_i32_e64 s[24:25], v32, v19
	s_and_b64 s[24:25], s[22:23], s[24:25]
	v_cmp_lt_u32_e64 s[22:23], s76, v32
	s_or_b64 s[22:23], s[74:75], s[22:23]
	v_or_b32_e32 v33, 2, v32
	s_and_b64 s[22:23], s[24:25], s[22:23]
	v_cmp_gt_i32_e64 s[24:25], v33, v18
	v_cmp_le_i32_e64 s[26:27], v33, v19
	v_or_b32_e32 v32, 3, v32
	s_and_b64 s[24:25], s[24:25], s[26:27]
	v_cmp_gt_i32_e64 s[26:27], v32, v18
	v_cmp_le_i32_e64 s[28:29], v32, v19
	s_and_b64 s[26:27], s[26:27], s[28:29]
	v_or_b32_e32 v32, s34, v161
	s_and_b64 s[20:21], s[30:31], s[20:21]
	s_and_b64 s[24:25], s[30:31], s[24:25]
	s_and_b64 s[26:27], s[30:31], s[26:27]
	v_cmp_gt_i32_e64 s[28:29], v32, v18
	v_cmp_le_i32_e64 s[30:31], v32, v19
	s_and_b64 s[28:29], s[28:29], s[30:31]
	s_cmpk_gt_u32 s34, 0x7f
	s_cselect_b64 s[30:31], -1, 0
	v_or_b32_e32 v24, s34, v91
	s_or_b64 s[40:41], s[74:75], s[30:31]
	v_cmp_ge_i32_e64 s[30:31], v32, v18
	v_cmp_lt_i32_e64 s[34:35], v32, v19
	s_and_b64 s[34:35], s[30:31], s[34:35]
; #define MFMA16(a, b, c) __builtin_amdgcn_mfma_f32_16x16x32_bf16((a), (b), (c), 0, 0, 0)
; __device__ __forceinline__ void swa_compute(SwaRaw& R, int b, int kvh, int nb, const bf16_t* P, const float* __restrict__ qg, const float* __restrict__ kg, const float* __restrict__ sinks, bf16_t* OB, LAS unsigned char* lds, int tid) {
;     ...
;         for (int j = 0; j < 10; ++j) { f32x4 acc = {0.f, 0.f, 0.f, 0.f};
; #pragma unroll
;             for (int ks = 0; ks < 2; ++ks) acc = MFMA16(ldfrag(Ks, 72, (kt0 + j) * 16 + fr, ks * 32 + 8 * fq), ldfrag(Qs, 72, wid * 16 + fr, ks * 32 + 8 * fq), acc);
;             s[j] = acc; }
;         const int qi = wid * 16 + fr; const float sink = sinks[hq]; float m = sink;
; #pragma unroll
;         for (int j = 0; j < 10; ++j)
; #pragma unroll
;             for (int r = 0; r < 4; ++r) { const int ki = (kt0 + j) * 16 + 4 * fq + r; const bool valid = (ki > qi) && (ki <= qi + 128) && ((nb > 0) || (ki >= 128));
;                 s[j][r] = valid ? s[j][r] : -INFINITY; m = fmaxf(m, s[j][r]); }
	v_cmp_lt_u32_e64 s[30:31], s76, v32
	s_or_b64 s[30:31], s[74:75], s[30:31]
	v_or_b32_e32 v33, 2, v32
	s_and_b64 s[30:31], s[34:35], s[30:31]
	v_cmp_gt_i32_e64 s[34:35], v33, v18
	v_cmp_le_i32_e64 s[36:37], v33, v19
	v_or_b32_e32 v32, 3, v32
	s_and_b64 s[34:35], s[34:35], s[36:37]
	v_cmp_gt_i32_e64 s[36:37], v32, v18
	v_cmp_le_i32_e64 s[38:39], v32, v19
	s_and_b64 s[36:37], s[36:37], s[38:39]
	v_or_b32_e32 v32, s42, v161
	s_and_b64 s[28:29], s[40:41], s[28:29]
	s_and_b64 s[34:35], s[40:41], s[34:35]
	s_and_b64 s[36:37], s[40:41], s[36:37]
	v_cmp_gt_i32_e64 s[38:39], v32, v18
	v_cmp_le_i32_e64 s[40:41], v32, v19
	s_and_b64 s[38:39], s[38:39], s[40:41]
	s_cmpk_gt_u32 s42, 0x7f
	s_cselect_b64 s[40:41], -1, 0
	v_or_b32_e32 v25, s42, v91
	s_or_b64 s[48:49], s[74:75], s[40:41]
	v_cmp_ge_i32_e64 s[40:41], v32, v18
	v_cmp_lt_i32_e64 s[42:43], v32, v19
	s_and_b64 s[42:43], s[40:41], s[42:43]
	v_cmp_lt_u32_e64 s[40:41], s76, v32
	s_or_b64 s[40:41], s[74:75], s[40:41]
	v_or_b32_e32 v33, 2, v32
	s_and_b64 s[40:41], s[42:43], s[40:41]
	v_cmp_gt_i32_e64 s[42:43], v33, v18
	v_cmp_le_i32_e64 s[44:45], v33, v19
	v_or_b32_e32 v32, 3, v32
	s_and_b64 s[42:43], s[42:43], s[44:45]
	v_cmp_gt_i32_e64 s[44:45], v32, v18
	v_cmp_le_i32_e64 s[46:47], v32, v19
	s_and_b64 s[44:45], s[44:45], s[46:47]
	v_or_b32_e32 v32, s50, v161
	s_and_b64 s[38:39], s[48:49], s[38:39]
	s_and_b64 s[42:43], s[48:49], s[42:43]
	s_and_b64 s[44:45], s[48:49], s[44:45]
	v_cmp_gt_i32_e64 s[46:47], v32, v18
	v_cmp_le_i32_e64 s[48:49], v32, v19
	s_and_b64 s[46:47], s[46:47], s[48:49]
	s_cmpk_gt_u32 s50, 0x7f
	s_cselect_b64 s[48:49], -1, 0
	v_or_b32_e32 v26, s50, v91
	s_or_b64 s[56:57], s[74:75], s[48:49]
	v_cmp_ge_i32_e64 s[48:49], v32, v18
	v_cmp_lt_i32_e64 s[50:51], v32, v19
	s_and_b64 s[50:51], s[48:49], s[50:51]
	v_cmp_lt_u32_e64 s[48:49], s76, v32
	s_or_b64 s[48:49], s[74:75], s[48:49]
	v_or_b32_e32 v33, 2, v32
	s_and_b64 s[48:49], s[50:51], s[48:49]
	v_cmp_gt_i32_e64 s[50:51], v33, v18
	v_cmp_le_i32_e64 s[52:53], v33, v19
	v_or_b32_e32 v32, 3, v32
	s_and_b64 s[50:51], s[50:51], s[52:53]
	v_cmp_gt_i32_e64 s[52:53], v32, v18
	v_cmp_le_i32_e64 s[54:55], v32, v19
	s_and_b64 s[52:53], s[52:53], s[54:55]
	v_or_b32_e32 v32, s58, v161
	s_and_b64 s[46:47], s[56:57], s[46:47]
	s_and_b64 s[50:51], s[56:57], s[50:51]
	s_and_b64 s[52:53], s[56:57], s[52:53]
	v_cmp_gt_i32_e64 s[54:55], v32, v18
	v_cmp_le_i32_e64 s[56:57], v32, v19
	s_and_b64 s[54:55], s[54:55], s[56:57]
	s_cmpk_gt_u32 s58, 0x7f
	v_or_b32_e32 v27, s58, v91
	v_or_b32_e32 v28, s66, v91
	v_or_b32_e32 v29, v31, v91
	v_or_b32_e32 v30, s78, v91
	s_cselect_b64 s[56:57], -1, 0
	v_mul_lo_u32 v20, v18, s59
	v_mul_lo_u32 v21, v21, s59
	v_mul_lo_u32 v22, v22, s59
	v_mul_lo_u32 v23, v23, s59
	v_mul_lo_u32 v24, v24, s59
	v_mul_lo_u32 v25, v25, s59
	v_mul_lo_u32 v26, v26, s59
	v_mul_lo_u32 v27, v27, s59
	v_mul_lo_u32 v28, v28, s59
	v_mul_lo_u32 v29, v29, s59
	v_mul_lo_u32 v30, v30, s59
	s_or_b64 s[64:65], s[74:75], s[56:57]
	v_cmp_ge_i32_e64 s[56:57], v32, v18
	v_cmp_lt_i32_e64 s[58:59], v32, v19
	s_and_b64 s[58:59], s[56:57], s[58:59]
	v_cmp_lt_u32_e64 s[56:57], s76, v32
	s_or_b64 s[56:57], s[74:75], s[56:57]
	v_or_b32_e32 v33, 2, v32
	s_and_b64 s[56:57], s[58:59], s[56:57]
	v_cmp_gt_i32_e64 s[58:59], v33, v18
	v_cmp_le_i32_e64 s[60:61], v33, v19
	v_or_b32_e32 v32, 3, v32
	s_and_b64 s[58:59], s[58:59], s[60:61]
	v_cmp_gt_i32_e64 s[60:61], v32, v18
	v_cmp_le_i32_e64 s[62:63], v32, v19
	s_and_b64 s[60:61], s[60:61], s[62:63]
	v_or_b32_e32 v32, s66, v161
	s_and_b64 s[54:55], s[64:65], s[54:55]
	s_and_b64 s[58:59], s[64:65], s[58:59]
	s_and_b64 s[60:61], s[64:65], s[60:61]
	v_cmp_gt_i32_e64 s[62:63], v32, v18
	v_cmp_le_i32_e64 s[64:65], v32, v19
	s_and_b64 s[62:63], s[62:63], s[64:65]
	s_cmpk_gt_u32 s66, 0x7f
	s_cselect_b64 s[64:65], -1, 0
	s_or_b64 s[72:73], s[74:75], s[64:65]
	v_cmp_ge_i32_e64 s[64:65], v32, v18
	v_cmp_lt_i32_e64 s[66:67], v32, v19
	s_and_b64 s[66:67], s[64:65], s[66:67]
	v_cmp_lt_u32_e64 s[64:65], s76, v32
	s_or_b64 s[64:65], s[74:75], s[64:65]
	v_or_b32_e32 v33, 2, v32
	s_and_b64 s[64:65], s[66:67], s[64:65]
	v_cmp_gt_i32_e64 s[66:67], v33, v18
	v_cmp_le_i32_e64 s[68:69], v33, v19
	v_or_b32_e32 v32, 3, v32
	s_and_b64 s[66:67], s[66:67], s[68:69]
	v_cmp_gt_i32_e64 s[68:69], v32, v18
	v_cmp_le_i32_e64 s[70:71], v32, v19
	s_and_b64 s[68:69], s[68:69], s[70:71]
	v_or_b32_e32 v31, v31, v161
	s_and_b64 s[62:63], s[72:73], s[62:63]
	s_and_b64 s[66:67], s[72:73], s[66:67]
	s_and_b64 s[68:69], s[72:73], s[68:69]
	v_cmp_gt_i32_e64 s[70:71], v31, v18
	v_cmp_le_i32_e64 s[72:73], v31, v19
	s_and_b64 s[70:71], s[70:71], s[72:73]
	s_or_b64 s[80:81], s[74:75], vcc
	v_cmp_ge_i32_e32 vcc, v31, v18
	v_cmp_lt_i32_e64 s[72:73], v31, v19
	s_and_b64 s[72:73], vcc, s[72:73]
	v_cmp_lt_u32_e32 vcc, s76, v31
	s_or_b64 s[74:75], s[74:75], vcc
	v_or_b32_e32 v32, 2, v31
	s_and_b64 s[72:73], s[72:73], s[74:75]
	v_cmp_gt_i32_e32 vcc, v32, v18
	v_cmp_le_i32_e64 s[74:75], v32, v19
	v_or_b32_e32 v31, 3, v31
	s_and_b64 s[74:75], vcc, s[74:75]
	v_cmp_gt_i32_e32 vcc, v31, v18
	v_cmp_le_i32_e64 s[76:77], v31, v19
	v_or_b32_e32 v31, s78, v161
	s_and_b64 s[76:77], vcc, s[76:77]
	v_cmp_gt_i32_e32 vcc, v31, v18
	v_cmp_le_i32_e64 s[78:79], v31, v19
	s_and_b64 s[70:71], s[80:81], s[70:71]
	s_and_b64 s[74:75], s[80:81], s[74:75]
	s_and_b64 s[76:77], s[80:81], s[76:77]
	s_and_b64 s[78:79], vcc, s[78:79]
	v_cmp_ge_i32_e32 vcc, v31, v18
	v_cmp_lt_i32_e64 s[80:81], v31, v19
	v_or_b32_e32 v32, 2, v31
	s_and_b64 s[80:81], vcc, s[80:81]
	v_cmp_gt_i32_e32 vcc, v32, v18
	v_cmp_le_i32_e64 s[82:83], v32, v19
	v_or_b32_e32 v31, 3, v31
	s_and_b64 s[82:83], vcc, s[82:83]
	v_cmp_gt_i32_e32 vcc, v31, v18
	v_cmp_le_i32_e64 s[84:85], v31, v19
	s_and_b64 s[84:85], vcc, s[84:85]
	s_add_u32 s86, s86, s89
	s_addc_u32 s87, s87, 0
	v_mov_b32_e32 v19, v1
	v_lshl_add_u64 v[34:35], s[86:87], 0, v[88:89]
	v_lshl_add_u64 v[18:19], s[86:87], 0, v[18:19]
	v_mad_u64_u32 v[36:37], vcc, v34, s96, v[0:1]
	v_lshlrev_b64 v[18:19], 11, v[18:19]
	v_add_u32_e32 v31, 0x3600, v66
	v_add_u32_e32 v32, 0x4800, v66
	v_mad_i32_i24 v37, v35, s96, v37
	v_or_b32_e32 v18, s88, v18
	v_lshl_add_u64 v[58:59], v[116:117], 0, v[36:37]
	v_lshl_add_u64 v[60:61], v[118:119], 0, v[18:19]
	s_mov_b64 s[86:87], 0
	v_add_u32_e32 v0, v184, v21
	v_add_u32_e32 v67, v184, v20
	v_add_u32_e32 v68, v184, v22
	v_add_u32_e32 v69, v184, v23
	v_add_u32_e32 v70, v184, v24
	v_add_u32_e32 v71, v184, v25
	v_add_u32_e32 v72, v184, v26
	v_add_u32_e32 v73, v184, v27
	v_add_u32_e32 v76, v184, v28
	v_add_u32_e32 v77, v184, v29
	v_add_u32_e32 v78, v184, v30
	v_add_u32_e32 v79, v165, v31
	v_add_u32_e32 v80, v165, v32
	s_waitcnt vmcnt(0)
	s_branch .LBB0_499

; __device__ __forceinline__ unsigned cvt_pk_bf16(float lo, float hi) { unsigned r; asm volatile("v_cvt_pk_bf16_f32 %0, %1, %2" : "=v"(r) : "v"(lo), "v"(hi)); return r; }
; __device__ __forceinline__ float bflo(unsigned w) { return __uint_as_float(w << 16); }
; __device__ __forceinline__ float bfhi(unsigned w) { return __uint_as_float(w & 0xffff0000u); }
; #define LAS __attribute__((address_space(3)))
; __device__ __forceinline__ void swa_compute(SwaRaw& R, int b, int kvh, int nb, const bf16_t* P, const float* __restrict__ qg, const float* __restrict__ kg, const float* __restrict__ sinks, bf16_t* OB, LAS unsigned char* lds, int tid) {
;     ...
;         for (int p = 0; p < 2; ++p) { const int row = (tid >> 3) + 64 * p; const u32x4 raw = R.q[p];
;             float x[8] = {bflo(raw.x), bfhi(raw.x), bflo(raw.y), bfhi(raw.y), bflo(raw.z), bfhi(raw.z), bflo(raw.w), bfhi(raw.w)};
;             float ss = 0.f;
; #pragma unroll
;             for (int e = 0; e < 8; ++e) ss += x[e] * x[e];
;             ss += __shfl_xor(ss, 1); ss += __shfl_xor(ss, 2); ss += __shfl_xor(ss, 4);
;             const float rs = 0.125f / sqrtf(ss * (1.0f / 64.0f) + EPS);
;             u32x4 w; w.x = cvt_pk_bf16(x[0] * rs * qg0.x, x[1] * rs * qg0.y); w.y = cvt_pk_bf16(x[2] * rs * qg0.z, x[3] * rs * qg0.w); w.z = cvt_pk_bf16(x[4] * rs * qg1.x, x[5] * rs * qg1.y); w.w = cvt_pk_bf16(x[6] * rs * qg1.z, x[7] * rs * qg1.w);
;             *(LAS u32x4*)(Qs + row * 72 + ch * 8) = w; }
;         if (g < 3) {
; #pragma unroll
;             for (int p = 0; p < 2; ++p) R.q[p] = *(const u32x4*)(P + (rq0 + (tid >> 3) + 64 * p) * PLD + 3072 + (hq + 1) * 64 + ch * 8);
;         }
.LBB0_499:
	s_waitcnt vmcnt(4)
	v_and_b32_e32 v21, 0xffff0000, v2
	v_lshlrev_b32_e32 v20, 16, v2
	v_mul_f32_e32 v28, v21, v21
	v_lshlrev_b32_e32 v24, 16, v3
	v_fmac_f32_e32 v28, v20, v20
	v_and_b32_e32 v25, 0xffff0000, v3
	v_fmac_f32_e32 v28, v24, v24
	v_lshlrev_b32_e32 v26, 16, v4
	v_fmac_f32_e32 v28, v25, v25
	v_and_b32_e32 v27, 0xffff0000, v4
	v_fmac_f32_e32 v28, v26, v26
	v_and_b32_e32 v22, 0xffff0000, v5
	v_lshlrev_b32_e32 v23, 16, v5
	v_fmac_f32_e32 v28, v27, v27
	v_pk_mul_f32 v[18:19], v[22:23], v[22:23]
	s_cmpk_eq_i32 s86, 0x180
	v_add_f32_e32 v19, v19, v28
	v_add_f32_e32 v18, v18, v19
	s_nop 1
	v_mov_b32_dpp v19, v18 quad_perm:[1,0,3,2] row_mask:0xf bank_mask:0xf
	s_waitcnt lgkmcnt(0)
	v_add_f32_e32 v18, v18, v19
	s_nop 1
	v_mov_b32_dpp v19, v18 quad_perm:[2,3,0,1] row_mask:0xf bank_mask:0xf
	s_waitcnt lgkmcnt(0)
	v_add_f32_e32 v18, v18, v19
	s_nop 1
	v_mov_b32_dpp v19, v18 row_half_mirror row_mask:0xf bank_mask:0xf
	s_waitcnt lgkmcnt(0)
	v_add_f32_e32 v18, v18, v19
	v_fmamk_f32 v18, v18, 0x3c800000, v95
	v_cmp_gt_f32_e32 vcc, s91, v18
	v_mul_f32_e32 v19, 0x4f800000, v18
	s_nop 0
	v_cndmask_b32_e32 v18, v18, v19, vcc
	v_sqrt_f32_e32 v19, v18
	s_nop 0
	v_add_u32_e32 v28, -1, v19
	v_fma_f32 v29, -v28, v19, v18
	v_cmp_ge_f32_e64 s[88:89], 0, v29
	v_add_u32_e32 v29, 1, v19
	s_nop 0
	v_cndmask_b32_e64 v28, v19, v28, s[88:89]
	v_fma_f32 v19, -v29, v19, v18
	v_cmp_lt_f32_e64 s[88:89], 0, v19
	s_nop 1
	v_cndmask_b32_e64 v19, v28, v29, s[88:89]
	v_mul_f32_e32 v28, 0x37800000, v19
	v_cndmask_b32_e32 v19, v19, v28, vcc
	v_cmp_class_f32_e32 vcc, v18, v172
	s_nop 1
	v_cndmask_b32_e32 v18, v19, v18, vcc
	v_div_scale_f32 v19, s[88:89], v18, v18, s93
	v_rcp_f32_e32 v28, v19
	s_nop 0
	v_fma_f32 v29, -v19, v28, 1.0
	v_fmac_f32_e32 v28, v29, v28
	v_div_scale_f32 v29, vcc, s93, v18, s93
	v_mul_f32_e32 v30, v29, v28
	v_fma_f32 v31, -v19, v30, v29
	v_fmac_f32_e32 v30, v31, v28
	v_fma_f32 v19, -v19, v30, v29
	v_div_fmas_f32 v19, v19, v28, v30
	v_div_fixup_f32 v28, v19, v18, s93
	v_mul_f32_e32 v18, v28, v20
	v_mul_f32_e32 v19, v28, v21
	v_mul_f32_e32 v18, v10, v18
	v_mul_f32_e32 v19, v11, v19
	v_cvt_pk_bf16_f32 v18, v18, v19
	v_mul_f32_e32 v19, v28, v24
	v_mul_f32_e32 v20, v28, v25
	v_mul_f32_e32 v19, v12, v19
	v_mul_f32_e32 v20, v13, v20
	v_cvt_pk_bf16_f32 v19, v19, v20
	v_mul_f32_e32 v20, v28, v26
	v_mul_f32_e32 v21, v28, v27
	v_mul_f32_e32 v20, v14, v20
	v_mul_f32_e32 v21, v15, v21
	v_cvt_pk_bf16_f32 v20, v20, v21
	v_mul_f32_e32 v21, v28, v23
	v_mul_f32_e32 v21, v16, v21
	v_mul_f32_e32 v22, v28, v22
	v_mul_f32_e32 v22, v17, v22
	v_cvt_pk_bf16_f32 v21, v21, v22
	ds_write_b128 v173, v[18:21]
	v_and_b32_e32 v21, 0xffff0000, v6
	v_lshlrev_b32_e32 v20, 16, v6
	v_mul_f32_e32 v28, v21, v21
	v_lshlrev_b32_e32 v24, 16, v7
	v_fmac_f32_e32 v28, v20, v20
	v_and_b32_e32 v25, 0xffff0000, v7
	v_fmac_f32_e32 v28, v24, v24
	v_lshlrev_b32_e32 v26, 16, v8
	v_fmac_f32_e32 v28, v25, v25
	v_and_b32_e32 v27, 0xffff0000, v8
	v_fmac_f32_e32 v28, v26, v26
	v_and_b32_e32 v22, 0xffff0000, v9
	v_lshlrev_b32_e32 v23, 16, v9
	v_fmac_f32_e32 v28, v27, v27
	v_pk_mul_f32 v[18:19], v[22:23], v[22:23]
	s_nop 0
	v_add_f32_e32 v19, v19, v28
	v_add_f32_e32 v18, v18, v19
	s_nop 1
	v_mov_b32_dpp v19, v18 quad_perm:[1,0,3,2] row_mask:0xf bank_mask:0xf
	s_waitcnt lgkmcnt(0)
	v_add_f32_e32 v18, v18, v19
	s_nop 1
	v_mov_b32_dpp v19, v18 quad_perm:[2,3,0,1] row_mask:0xf bank_mask:0xf
	s_waitcnt lgkmcnt(0)
	v_add_f32_e32 v18, v18, v19
	s_nop 1
	v_mov_b32_dpp v19, v18 row_half_mirror row_mask:0xf bank_mask:0xf
	s_waitcnt lgkmcnt(0)
	v_add_f32_e32 v18, v18, v19
	v_fmamk_f32 v18, v18, 0x3c800000, v95
	v_cmp_gt_f32_e32 vcc, s91, v18
	v_mul_f32_e32 v19, 0x4f800000, v18
	s_nop 0
	v_cndmask_b32_e32 v18, v18, v19, vcc
	v_sqrt_f32_e32 v19, v18
	s_nop 0
	v_add_u32_e32 v28, -1, v19
	v_fma_f32 v29, -v28, v19, v18
	v_cmp_ge_f32_e64 s[88:89], 0, v29
	v_add_u32_e32 v29, 1, v19
	s_nop 0
	v_cndmask_b32_e64 v28, v19, v28, s[88:89]
	v_fma_f32 v19, -v29, v19, v18
	v_cmp_lt_f32_e64 s[88:89], 0, v19
	s_nop 1
	v_cndmask_b32_e64 v19, v28, v29, s[88:89]
	v_mul_f32_e32 v28, 0x37800000, v19
	v_cndmask_b32_e32 v19, v19, v28, vcc
	v_cmp_class_f32_e32 vcc, v18, v172
	s_nop 1
	v_cndmask_b32_e32 v18, v19, v18, vcc
	v_div_scale_f32 v19, s[88:89], v18, v18, s93
	v_rcp_f32_e32 v28, v19
	s_nop 0
	v_fma_f32 v29, -v19, v28, 1.0
	v_fmac_f32_e32 v28, v29, v28
	v_div_scale_f32 v29, vcc, s93, v18, s93
	v_mul_f32_e32 v30, v29, v28
	v_fma_f32 v31, -v19, v30, v29
	v_fmac_f32_e32 v30, v31, v28
	v_fma_f32 v19, -v19, v30, v29
	v_div_fmas_f32 v19, v19, v28, v30
	v_div_fixup_f32 v28, v19, v18, s93
	v_mul_f32_e32 v18, v28, v20
	v_mul_f32_e32 v19, v28, v21
	v_mul_f32_e32 v18, v10, v18
	v_mul_f32_e32 v19, v11, v19
	v_cvt_pk_bf16_f32 v18, v18, v19
	v_mul_f32_e32 v19, v28, v24
	v_mul_f32_e32 v20, v28, v25
	v_mul_f32_e32 v19, v12, v19
	v_mul_f32_e32 v20, v13, v20
	v_cvt_pk_bf16_f32 v19, v19, v20
	v_mul_f32_e32 v20, v28, v26
	v_mul_f32_e32 v21, v28, v27
	v_mul_f32_e32 v20, v14, v20
	v_mul_f32_e32 v21, v15, v21
	v_cvt_pk_bf16_f32 v20, v20, v21
	v_mul_f32_e32 v21, v28, v23
	v_mul_f32_e32 v21, v16, v21
	v_mul_f32_e32 v22, v28, v22
	v_mul_f32_e32 v22, v17, v22
	v_cvt_pk_bf16_f32 v21, v21, v22
	ds_write_b128 v173, v[18:21] offset:9216
	s_cbranch_scc1 .LBB0_498
	v_lshl_add_u64 v[2:3], v[58:59], 0, s[86:87]
	v_add_co_u32_e32 v4, vcc, 0xb801000, v2
	s_nop 1
	v_addc_co_u32_e32 v5, vcc, 0, v3, vcc
	v_add_co_u32_e32 v6, vcc, 0xb911000, v2
	s_nop 1
	v_addc_co_u32_e32 v7, vcc, 0, v3, vcc
	global_load_dwordx4 v[2:5], v[4:5], off offset:2176
	s_nop 0
	global_load_dwordx4 v[6:9], v[6:7], off offset:2176
	s_branch .LBB0_498
